# GEMM K-loops: LDS-DMA addresses on SALU (saddr form) in the 4 FFN loops, no s_setprio and no redundant waits inside the MFMA bursts of all 9 loops; bit-identical outputs
# speedup vs baseline: 1.0034x; 1.0034x over previous
.LBB0_182:
	ds_read_b128 v[144:147], v153 offset:0
	ds_read_b128 v[156:159], v153 offset:1024
	ds_read_b128 v[160:163], v153 offset:2048
	ds_read_b128 v[164:167], v153 offset:3072
	ds_read_b128 v[168:171], v154 offset:0
	ds_read_b128 v[172:175], v154 offset:1024
	ds_read_b128 v[176:179], v154 offset:2048
	ds_read_b128 v[180:183], v154 offset:3072
	s_add_u32 s30, s72, 0xfff00080
	s_addc_u32 s31, s73, -1
	s_cmp_eq_u32 s41, 60
	s_cselect_b32 s31, s13, s31
	s_cselect_b32 s30, s37, s30
	s_cselect_b32 s75, s11, s40
	s_cselect_b32 s74, s38, s39
	ds_read_b128 v[184:187], v155 offset:0
	ds_read_b128 v[188:191], v155 offset:1024
	ds_read_b128 v[192:195], v155 offset:2048
	ds_read_b128 v[196:199], v155 offset:3072
	ds_read_b128 v[200:203], v155 offset:4096
	ds_read_b128 v[204:207], v155 offset:5120
	ds_read_b128 v[208:211], v155 offset:6144
	ds_read_b128 v[212:215], v155 offset:7168
	s_add_i32 m0, s29, 0xc000
	s_nop 0
	global_load_lds_dwordx4 v136, s[72:73]
	s_add_i32 m0, s29, 0xe000
	s_nop 0
	global_load_lds_dwordx4 v138, s[72:73]
	s_waitcnt vmcnt(8)
	s_waitcnt lgkmcnt(0)
	s_barrier
	v_mfma_f32_16x16x32_bf16 v[124:127], v[144:147], v[184:187], v[124:127]
	v_mfma_f32_16x16x32_bf16 v[120:123], v[160:163], v[184:187], v[120:123]
	v_mfma_f32_16x16x32_bf16 v[108:111], v[144:147], v[192:195], v[108:111]
	v_mfma_f32_16x16x32_bf16 v[104:107], v[160:163], v[192:195], v[104:107]
	v_mfma_f32_16x16x32_bf16 v[92:95], v[144:147], v[200:203], v[92:95]
	v_mfma_f32_16x16x32_bf16 v[88:91], v[160:163], v[200:203], v[88:91]
	v_mfma_f32_16x16x32_bf16 v[76:79], v[144:147], v[208:211], v[76:79]
	v_mfma_f32_16x16x32_bf16 v[72:75], v[160:163], v[208:211], v[72:75]
	v_mfma_f32_16x16x32_bf16 v[124:127], v[156:159], v[188:191], v[124:127]
	v_mfma_f32_16x16x32_bf16 v[120:123], v[164:167], v[188:191], v[120:123]
	v_mfma_f32_16x16x32_bf16 v[108:111], v[156:159], v[196:199], v[108:111]
	v_mfma_f32_16x16x32_bf16 v[104:107], v[164:167], v[196:199], v[104:107]
	v_mfma_f32_16x16x32_bf16 v[92:95], v[156:159], v[204:207], v[92:95]
	v_mfma_f32_16x16x32_bf16 v[88:91], v[164:167], v[204:207], v[88:91]
	v_mfma_f32_16x16x32_bf16 v[76:79], v[156:159], v[212:215], v[76:79]
	v_mfma_f32_16x16x32_bf16 v[72:75], v[164:167], v[212:215], v[72:75]
	v_mfma_f32_16x16x32_bf16 v[116:119], v[168:171], v[184:187], v[116:119]
	v_mfma_f32_16x16x32_bf16 v[112:115], v[176:179], v[184:187], v[112:115]
	v_mfma_f32_16x16x32_bf16 v[100:103], v[168:171], v[192:195], v[100:103]
	v_mfma_f32_16x16x32_bf16 v[96:99], v[176:179], v[192:195], v[96:99]
	v_mfma_f32_16x16x32_bf16 v[84:87], v[168:171], v[200:203], v[84:87]
	v_mfma_f32_16x16x32_bf16 v[80:83], v[176:179], v[200:203], v[80:83]
	v_mfma_f32_16x16x32_bf16 v[68:71], v[168:171], v[208:211], v[68:71]
	v_mfma_f32_16x16x32_bf16 v[64:67], v[176:179], v[208:211], v[64:67]
	v_mfma_f32_16x16x32_bf16 v[116:119], v[172:175], v[188:191], v[116:119]
	v_mfma_f32_16x16x32_bf16 v[112:115], v[180:183], v[188:191], v[112:115]
	v_mfma_f32_16x16x32_bf16 v[100:103], v[172:175], v[196:199], v[100:103]
	v_mfma_f32_16x16x32_bf16 v[96:99], v[180:183], v[196:199], v[96:99]
	v_mfma_f32_16x16x32_bf16 v[84:87], v[172:175], v[204:207], v[84:87]
	v_mfma_f32_16x16x32_bf16 v[80:83], v[180:183], v[204:207], v[80:83]
	v_mfma_f32_16x16x32_bf16 v[68:71], v[172:175], v[212:215], v[68:71]
	v_mfma_f32_16x16x32_bf16 v[64:67], v[180:183], v[212:215], v[64:67]
	s_barrier
	s_add_u32 s42, s74, 0x100000
	s_addc_u32 s43, s75, 0
	ds_read_b128 v[184:187], v155 offset:16384
	ds_read_b128 v[188:191], v155 offset:17408
	ds_read_b128 v[192:195], v155 offset:18432
	ds_read_b128 v[196:199], v155 offset:19456
	ds_read_b128 v[200:203], v155 offset:20480
	ds_read_b128 v[204:207], v155 offset:21504
	ds_read_b128 v[208:211], v155 offset:22528
	ds_read_b128 v[212:215], v155 offset:23552
	s_add_i32 m0, s29, 0x10000
	s_nop 0
	global_load_lds_dwordx4 v130, s[74:75]
	s_add_i32 m0, s29, 0x12000
	s_nop 0
	global_load_lds_dwordx4 v134, s[74:75]
	s_add_i32 m0, s29, 0x14000
	s_nop 0
	global_load_lds_dwordx4 v130, s[42:43]
	s_add_i32 m0, s29, 0x16000
	s_nop 0
	global_load_lds_dwordx4 v134, s[42:43]
	s_add_i32 m0, s29, 0x0
	s_nop 0
	global_load_lds_dwordx4 v128, s[30:31]
	s_add_i32 m0, s29, 0x2000
	s_nop 0
	global_load_lds_dwordx4 v132, s[30:31]
	s_waitcnt vmcnt(8)
	s_waitcnt lgkmcnt(0)
	s_barrier
	v_mfma_f32_16x16x32_bf16 v[60:63], v[144:147], v[184:187], v[60:63]
	v_mfma_f32_16x16x32_bf16 v[56:59], v[160:163], v[184:187], v[56:59]
	v_mfma_f32_16x16x32_bf16 v[44:47], v[144:147], v[192:195], v[44:47]
	v_mfma_f32_16x16x32_bf16 v[40:43], v[160:163], v[192:195], v[40:43]
	v_mfma_f32_16x16x32_bf16 v[28:31], v[144:147], v[200:203], v[28:31]
	v_mfma_f32_16x16x32_bf16 v[24:27], v[160:163], v[200:203], v[24:27]
	v_mfma_f32_16x16x32_bf16 v[12:15], v[144:147], v[208:211], v[12:15]
	v_mfma_f32_16x16x32_bf16 v[8:11], v[160:163], v[208:211], v[8:11]
	v_mfma_f32_16x16x32_bf16 v[60:63], v[156:159], v[188:191], v[60:63]
	v_mfma_f32_16x16x32_bf16 v[56:59], v[164:167], v[188:191], v[56:59]
	v_mfma_f32_16x16x32_bf16 v[44:47], v[156:159], v[196:199], v[44:47]
	v_mfma_f32_16x16x32_bf16 v[40:43], v[164:167], v[196:199], v[40:43]
	v_mfma_f32_16x16x32_bf16 v[28:31], v[156:159], v[204:207], v[28:31]
	v_mfma_f32_16x16x32_bf16 v[24:27], v[164:167], v[204:207], v[24:27]
	v_mfma_f32_16x16x32_bf16 v[12:15], v[156:159], v[212:215], v[12:15]
	v_mfma_f32_16x16x32_bf16 v[8:11], v[164:167], v[212:215], v[8:11]
	v_mfma_f32_16x16x32_bf16 v[52:55], v[168:171], v[184:187], v[52:55]
	v_mfma_f32_16x16x32_bf16 v[48:51], v[176:179], v[184:187], v[48:51]
	v_mfma_f32_16x16x32_bf16 v[36:39], v[168:171], v[192:195], v[36:39]
	v_mfma_f32_16x16x32_bf16 v[32:35], v[176:179], v[192:195], v[32:35]
	v_mfma_f32_16x16x32_bf16 v[20:23], v[168:171], v[200:203], v[20:23]
	v_mfma_f32_16x16x32_bf16 v[16:19], v[176:179], v[200:203], v[16:19]
	v_mfma_f32_16x16x32_bf16 v[4:7], v[168:171], v[208:211], v[4:7]
	v_mfma_f32_16x16x32_bf16 v[0:3], v[176:179], v[208:211], v[0:3]
	v_mfma_f32_16x16x32_bf16 v[52:55], v[172:175], v[188:191], v[52:55]
	v_mfma_f32_16x16x32_bf16 v[48:51], v[180:183], v[188:191], v[48:51]
	v_mfma_f32_16x16x32_bf16 v[36:39], v[172:175], v[196:199], v[36:39]
	v_mfma_f32_16x16x32_bf16 v[32:35], v[180:183], v[196:199], v[32:35]
	v_mfma_f32_16x16x32_bf16 v[20:23], v[172:175], v[204:207], v[20:23]
	v_mfma_f32_16x16x32_bf16 v[16:19], v[180:183], v[204:207], v[16:19]
	v_mfma_f32_16x16x32_bf16 v[4:7], v[172:175], v[212:215], v[4:7]
	v_mfma_f32_16x16x32_bf16 v[0:3], v[180:183], v[212:215], v[0:3]
	s_barrier
	s_add_u32 s98, s30, 0x100000
	s_addc_u32 s99, s31, 0
	ds_read_b128 v[144:147], v153 offset:32768
	ds_read_b128 v[156:159], v153 offset:33792
	ds_read_b128 v[160:163], v153 offset:34816
	ds_read_b128 v[164:167], v153 offset:35840
	ds_read_b128 v[168:171], v154 offset:32768
	ds_read_b128 v[172:175], v154 offset:33792
	ds_read_b128 v[176:179], v154 offset:34816
	ds_read_b128 v[180:183], v154 offset:35840
	ds_read_b128 v[184:187], v155 offset:32768
	ds_read_b128 v[188:191], v155 offset:33792
	ds_read_b128 v[192:195], v155 offset:34816
	ds_read_b128 v[196:199], v155 offset:35840
	ds_read_b128 v[200:203], v155 offset:36864
	ds_read_b128 v[204:207], v155 offset:37888
	ds_read_b128 v[208:211], v155 offset:38912
	ds_read_b128 v[212:215], v155 offset:39936
	s_add_i32 m0, s29, 0x4000
	s_nop 0
	global_load_lds_dwordx4 v128, s[98:99]
	s_add_i32 m0, s29, 0x6000
	s_nop 0
	global_load_lds_dwordx4 v132, s[98:99]
	s_waitcnt vmcnt(8)
	s_waitcnt lgkmcnt(0)
	s_barrier
	v_mfma_f32_16x16x32_bf16 v[124:127], v[144:147], v[184:187], v[124:127]
	v_mfma_f32_16x16x32_bf16 v[120:123], v[160:163], v[184:187], v[120:123]
	v_mfma_f32_16x16x32_bf16 v[108:111], v[144:147], v[192:195], v[108:111]
	v_mfma_f32_16x16x32_bf16 v[104:107], v[160:163], v[192:195], v[104:107]
	v_mfma_f32_16x16x32_bf16 v[92:95], v[144:147], v[200:203], v[92:95]
	v_mfma_f32_16x16x32_bf16 v[88:91], v[160:163], v[200:203], v[88:91]
	v_mfma_f32_16x16x32_bf16 v[76:79], v[144:147], v[208:211], v[76:79]
	v_mfma_f32_16x16x32_bf16 v[72:75], v[160:163], v[208:211], v[72:75]
	v_mfma_f32_16x16x32_bf16 v[124:127], v[156:159], v[188:191], v[124:127]
	v_mfma_f32_16x16x32_bf16 v[120:123], v[164:167], v[188:191], v[120:123]
	v_mfma_f32_16x16x32_bf16 v[108:111], v[156:159], v[196:199], v[108:111]
	v_mfma_f32_16x16x32_bf16 v[104:107], v[164:167], v[196:199], v[104:107]
	v_mfma_f32_16x16x32_bf16 v[92:95], v[156:159], v[204:207], v[92:95]
	v_mfma_f32_16x16x32_bf16 v[88:91], v[164:167], v[204:207], v[88:91]
	v_mfma_f32_16x16x32_bf16 v[76:79], v[156:159], v[212:215], v[76:79]
	v_mfma_f32_16x16x32_bf16 v[72:75], v[164:167], v[212:215], v[72:75]
	v_mfma_f32_16x16x32_bf16 v[116:119], v[168:171], v[184:187], v[116:119]
	v_mfma_f32_16x16x32_bf16 v[112:115], v[176:179], v[184:187], v[112:115]
	v_mfma_f32_16x16x32_bf16 v[100:103], v[168:171], v[192:195], v[100:103]
	v_mfma_f32_16x16x32_bf16 v[96:99], v[176:179], v[192:195], v[96:99]
	v_mfma_f32_16x16x32_bf16 v[84:87], v[168:171], v[200:203], v[84:87]
	v_mfma_f32_16x16x32_bf16 v[80:83], v[176:179], v[200:203], v[80:83]
	v_mfma_f32_16x16x32_bf16 v[68:71], v[168:171], v[208:211], v[68:71]
	v_mfma_f32_16x16x32_bf16 v[64:67], v[176:179], v[208:211], v[64:67]
	v_mfma_f32_16x16x32_bf16 v[116:119], v[172:175], v[188:191], v[116:119]
	v_mfma_f32_16x16x32_bf16 v[112:115], v[180:183], v[188:191], v[112:115]
	v_mfma_f32_16x16x32_bf16 v[100:103], v[172:175], v[196:199], v[100:103]
	v_mfma_f32_16x16x32_bf16 v[96:99], v[180:183], v[196:199], v[96:99]
	v_mfma_f32_16x16x32_bf16 v[84:87], v[172:175], v[204:207], v[84:87]
	v_mfma_f32_16x16x32_bf16 v[80:83], v[180:183], v[204:207], v[80:83]
	v_mfma_f32_16x16x32_bf16 v[68:71], v[172:175], v[212:215], v[68:71]
	v_mfma_f32_16x16x32_bf16 v[64:67], v[180:183], v[212:215], v[64:67]
	s_barrier
	s_add_u32 s100, s74, 0x80
	s_addc_u32 s101, s75, 0
	s_add_u32 s42, s74, 0x100080
	s_addc_u32 s43, s75, 0
	s_add_u32 s98, s30, 0x80
	s_addc_u32 s99, s31, 0
	ds_read_b128 v[184:187], v155 offset:49152
	ds_read_b128 v[188:191], v155 offset:50176
	ds_read_b128 v[192:195], v155 offset:51200
	ds_read_b128 v[196:199], v155 offset:52224
	ds_read_b128 v[200:203], v155 offset:53248
	ds_read_b128 v[204:207], v155 offset:54272
	ds_read_b128 v[208:211], v155 offset:55296
	ds_read_b128 v[212:215], v155 offset:56320
	s_add_i32 m0, s29, 0x18000
	s_nop 0
	global_load_lds_dwordx4 v130, s[100:101]
	s_add_i32 m0, s29, 0x1a000
	s_nop 0
	global_load_lds_dwordx4 v134, s[100:101]
	s_add_i32 m0, s29, 0x1c000
	s_nop 0
	global_load_lds_dwordx4 v130, s[42:43]
	s_add_i32 m0, s29, 0x1e000
	s_nop 0
	global_load_lds_dwordx4 v134, s[42:43]
	s_add_i32 m0, s29, 0x8000
	s_nop 0
	global_load_lds_dwordx4 v128, s[98:99]
	s_add_i32 m0, s29, 0xa000
	s_nop 0
	global_load_lds_dwordx4 v132, s[98:99]
	s_waitcnt vmcnt(8)
	s_waitcnt lgkmcnt(0)
	s_barrier
	v_mfma_f32_16x16x32_bf16 v[60:63], v[144:147], v[184:187], v[60:63]
	v_mfma_f32_16x16x32_bf16 v[56:59], v[160:163], v[184:187], v[56:59]
	v_mfma_f32_16x16x32_bf16 v[44:47], v[144:147], v[192:195], v[44:47]
	v_mfma_f32_16x16x32_bf16 v[40:43], v[160:163], v[192:195], v[40:43]
	v_mfma_f32_16x16x32_bf16 v[28:31], v[144:147], v[200:203], v[28:31]
	v_mfma_f32_16x16x32_bf16 v[24:27], v[160:163], v[200:203], v[24:27]
	v_mfma_f32_16x16x32_bf16 v[12:15], v[144:147], v[208:211], v[12:15]
	v_mfma_f32_16x16x32_bf16 v[8:11], v[160:163], v[208:211], v[8:11]
	v_mfma_f32_16x16x32_bf16 v[60:63], v[156:159], v[188:191], v[60:63]
	v_mfma_f32_16x16x32_bf16 v[56:59], v[164:167], v[188:191], v[56:59]
	v_mfma_f32_16x16x32_bf16 v[44:47], v[156:159], v[196:199], v[44:47]
	v_mfma_f32_16x16x32_bf16 v[40:43], v[164:167], v[196:199], v[40:43]
	v_mfma_f32_16x16x32_bf16 v[28:31], v[156:159], v[204:207], v[28:31]
	v_mfma_f32_16x16x32_bf16 v[24:27], v[164:167], v[204:207], v[24:27]
	v_mfma_f32_16x16x32_bf16 v[12:15], v[156:159], v[212:215], v[12:15]
	v_mfma_f32_16x16x32_bf16 v[8:11], v[164:167], v[212:215], v[8:11]
	v_mfma_f32_16x16x32_bf16 v[52:55], v[168:171], v[184:187], v[52:55]
	v_mfma_f32_16x16x32_bf16 v[48:51], v[176:179], v[184:187], v[48:51]
	v_mfma_f32_16x16x32_bf16 v[36:39], v[168:171], v[192:195], v[36:39]
	v_mfma_f32_16x16x32_bf16 v[32:35], v[176:179], v[192:195], v[32:35]
	v_mfma_f32_16x16x32_bf16 v[20:23], v[168:171], v[200:203], v[20:23]
	v_mfma_f32_16x16x32_bf16 v[16:19], v[176:179], v[200:203], v[16:19]
	v_mfma_f32_16x16x32_bf16 v[4:7], v[168:171], v[208:211], v[4:7]
	v_mfma_f32_16x16x32_bf16 v[0:3], v[176:179], v[208:211], v[0:3]
	v_mfma_f32_16x16x32_bf16 v[52:55], v[172:175], v[188:191], v[52:55]
	v_mfma_f32_16x16x32_bf16 v[48:51], v[180:183], v[188:191], v[48:51]
	v_mfma_f32_16x16x32_bf16 v[36:39], v[172:175], v[196:199], v[36:39]
	v_mfma_f32_16x16x32_bf16 v[32:35], v[180:183], v[196:199], v[32:35]
	v_mfma_f32_16x16x32_bf16 v[20:23], v[172:175], v[204:207], v[20:23]
	v_mfma_f32_16x16x32_bf16 v[16:19], v[180:183], v[204:207], v[16:19]
	v_mfma_f32_16x16x32_bf16 v[4:7], v[172:175], v[212:215], v[4:7]
	v_mfma_f32_16x16x32_bf16 v[0:3], v[180:183], v[212:215], v[0:3]
	s_barrier
	s_add_i32 s41, s41, 2
	s_add_u32 s72, s72, 0x100
	s_addc_u32 s73, s73, 0
	s_add_u32 s39, s39, 0x100
	s_addc_u32 s40, s40, 0
	s_cmp_gt_u32 s41, 61
	s_cbranch_scc0 .LBB0_182
	s_and_b64 vcc, exec, s[6:7]
	s_cbranch_vccz .LBB0_185
	s_barrier

.LBB0_401:
	ds_read_b128 v[142:145], v169 offset:0
	ds_read_b128 v[146:149], v169 offset:1024
	ds_read_b128 v[150:153], v169 offset:2048
	ds_read_b128 v[154:157], v169 offset:3072
	ds_read_b128 v[158:161], v170 offset:0
	ds_read_b128 v[162:165], v170 offset:1024
	ds_read_b128 v[172:175], v170 offset:2048
	ds_read_b128 v[176:179], v170 offset:3072
	s_add_i32 s38, s30, 2
	s_add_u32 s46, s44, 0x100
	s_addc_u32 s47, s45, 0
	s_cmp_eq_u32 s17, s30
	s_cselect_b32 s30, s34, s46
	s_cselect_b32 s31, s35, s47
	s_cselect_b32 s53, s41, s37
	s_cselect_b32 s52, s40, s36
	ds_read_b128 v[180:183], v171 offset:0
	ds_read_b128 v[184:187], v171 offset:1024
	ds_read_b128 v[188:191], v171 offset:2048
	ds_read_b128 v[192:195], v171 offset:3072
	ds_read_b128 v[196:199], v171 offset:4096
	ds_read_b128 v[200:203], v171 offset:5120
	ds_read_b128 v[204:207], v171 offset:6144
	ds_read_b128 v[208:211], v171 offset:7168
	s_add_i32 m0, s60, 0xc000
	s_nop 0
	global_load_lds_dwordx4 v136, s[44:45]
	s_add_i32 m0, s60, 0xe000
	s_nop 0
	global_load_lds_dwordx4 v138, s[44:45]
	s_waitcnt vmcnt(8)
	s_waitcnt lgkmcnt(0)
	s_barrier
	v_mfma_f32_16x16x32_bf16 v[124:127], v[142:145], v[180:183], v[124:127]
	v_mfma_f32_16x16x32_bf16 v[120:123], v[150:153], v[180:183], v[120:123]
	v_mfma_f32_16x16x32_bf16 v[108:111], v[142:145], v[188:191], v[108:111]
	v_mfma_f32_16x16x32_bf16 v[104:107], v[150:153], v[188:191], v[104:107]
	v_mfma_f32_16x16x32_bf16 v[92:95], v[142:145], v[196:199], v[92:95]
	v_mfma_f32_16x16x32_bf16 v[88:91], v[150:153], v[196:199], v[88:91]
	v_mfma_f32_16x16x32_bf16 v[76:79], v[142:145], v[204:207], v[76:79]
	v_mfma_f32_16x16x32_bf16 v[72:75], v[150:153], v[204:207], v[72:75]
	v_mfma_f32_16x16x32_bf16 v[124:127], v[146:149], v[184:187], v[124:127]
	v_mfma_f32_16x16x32_bf16 v[120:123], v[154:157], v[184:187], v[120:123]
	v_mfma_f32_16x16x32_bf16 v[108:111], v[146:149], v[192:195], v[108:111]
	v_mfma_f32_16x16x32_bf16 v[104:107], v[154:157], v[192:195], v[104:107]
	v_mfma_f32_16x16x32_bf16 v[92:95], v[146:149], v[200:203], v[92:95]
	v_mfma_f32_16x16x32_bf16 v[88:91], v[154:157], v[200:203], v[88:91]
	v_mfma_f32_16x16x32_bf16 v[76:79], v[146:149], v[208:211], v[76:79]
	v_mfma_f32_16x16x32_bf16 v[72:75], v[154:157], v[208:211], v[72:75]
	v_mfma_f32_16x16x32_bf16 v[116:119], v[158:161], v[180:183], v[116:119]
	v_mfma_f32_16x16x32_bf16 v[112:115], v[172:175], v[180:183], v[112:115]
	v_mfma_f32_16x16x32_bf16 v[100:103], v[158:161], v[188:191], v[100:103]
	v_mfma_f32_16x16x32_bf16 v[96:99], v[172:175], v[188:191], v[96:99]
	v_mfma_f32_16x16x32_bf16 v[84:87], v[158:161], v[196:199], v[84:87]
	v_mfma_f32_16x16x32_bf16 v[80:83], v[172:175], v[196:199], v[80:83]
	v_mfma_f32_16x16x32_bf16 v[68:71], v[158:161], v[204:207], v[68:71]
	v_mfma_f32_16x16x32_bf16 v[64:67], v[172:175], v[204:207], v[64:67]
	v_mfma_f32_16x16x32_bf16 v[116:119], v[162:165], v[184:187], v[116:119]
	v_mfma_f32_16x16x32_bf16 v[112:115], v[176:179], v[184:187], v[112:115]
	v_mfma_f32_16x16x32_bf16 v[100:103], v[162:165], v[192:195], v[100:103]
	v_mfma_f32_16x16x32_bf16 v[96:99], v[176:179], v[192:195], v[96:99]
	v_mfma_f32_16x16x32_bf16 v[84:87], v[162:165], v[200:203], v[84:87]
	v_mfma_f32_16x16x32_bf16 v[80:83], v[176:179], v[200:203], v[80:83]
	v_mfma_f32_16x16x32_bf16 v[68:71], v[162:165], v[208:211], v[68:71]
	v_mfma_f32_16x16x32_bf16 v[64:67], v[176:179], v[208:211], v[64:67]
	s_barrier
	s_add_u32 s42, s52, 0x2b0000
	s_addc_u32 s43, s53, 0
	ds_read_b128 v[180:183], v171 offset:16384
	ds_read_b128 v[184:187], v171 offset:17408
	ds_read_b128 v[188:191], v171 offset:18432
	ds_read_b128 v[192:195], v171 offset:19456
	ds_read_b128 v[196:199], v171 offset:20480
	ds_read_b128 v[200:203], v171 offset:21504
	ds_read_b128 v[204:207], v171 offset:22528
	ds_read_b128 v[208:211], v171 offset:23552
	s_add_i32 m0, s60, 0x10000
	s_nop 0
	global_load_lds_dwordx4 v130, s[52:53]
	s_add_i32 m0, s60, 0x12000
	s_nop 0
	global_load_lds_dwordx4 v134, s[52:53]
	s_add_i32 m0, s60, 0x14000
	s_nop 0
	global_load_lds_dwordx4 v130, s[42:43]
	s_add_i32 m0, s60, 0x16000
	s_nop 0
	global_load_lds_dwordx4 v134, s[42:43]
	s_add_i32 m0, s60, 0x0
	s_nop 0
	global_load_lds_dwordx4 v128, s[30:31]
	s_add_i32 m0, s60, 0x2000
	s_nop 0
	global_load_lds_dwordx4 v132, s[30:31]
	s_waitcnt vmcnt(8)
	s_waitcnt lgkmcnt(0)
	s_barrier
	v_mfma_f32_16x16x32_bf16 v[60:63], v[142:145], v[180:183], v[60:63]
	v_mfma_f32_16x16x32_bf16 v[56:59], v[150:153], v[180:183], v[56:59]
	v_mfma_f32_16x16x32_bf16 v[44:47], v[142:145], v[188:191], v[44:47]
	v_mfma_f32_16x16x32_bf16 v[40:43], v[150:153], v[188:191], v[40:43]
	v_mfma_f32_16x16x32_bf16 v[28:31], v[142:145], v[196:199], v[28:31]
	v_mfma_f32_16x16x32_bf16 v[24:27], v[150:153], v[196:199], v[24:27]
	v_mfma_f32_16x16x32_bf16 v[12:15], v[142:145], v[204:207], v[12:15]
	v_mfma_f32_16x16x32_bf16 v[8:11], v[150:153], v[204:207], v[8:11]
	v_mfma_f32_16x16x32_bf16 v[60:63], v[146:149], v[184:187], v[60:63]
	v_mfma_f32_16x16x32_bf16 v[56:59], v[154:157], v[184:187], v[56:59]
	v_mfma_f32_16x16x32_bf16 v[44:47], v[146:149], v[192:195], v[44:47]
	v_mfma_f32_16x16x32_bf16 v[40:43], v[154:157], v[192:195], v[40:43]
	v_mfma_f32_16x16x32_bf16 v[28:31], v[146:149], v[200:203], v[28:31]
	v_mfma_f32_16x16x32_bf16 v[24:27], v[154:157], v[200:203], v[24:27]
	v_mfma_f32_16x16x32_bf16 v[12:15], v[146:149], v[208:211], v[12:15]
	v_mfma_f32_16x16x32_bf16 v[8:11], v[154:157], v[208:211], v[8:11]
	v_mfma_f32_16x16x32_bf16 v[52:55], v[158:161], v[180:183], v[52:55]
	v_mfma_f32_16x16x32_bf16 v[48:51], v[172:175], v[180:183], v[48:51]
	v_mfma_f32_16x16x32_bf16 v[36:39], v[158:161], v[188:191], v[36:39]
	v_mfma_f32_16x16x32_bf16 v[32:35], v[172:175], v[188:191], v[32:35]
	v_mfma_f32_16x16x32_bf16 v[20:23], v[158:161], v[196:199], v[20:23]
	v_mfma_f32_16x16x32_bf16 v[16:19], v[172:175], v[196:199], v[16:19]
	v_mfma_f32_16x16x32_bf16 v[4:7], v[158:161], v[204:207], v[4:7]
	v_mfma_f32_16x16x32_bf16 v[0:3], v[172:175], v[204:207], v[0:3]
	v_mfma_f32_16x16x32_bf16 v[52:55], v[162:165], v[184:187], v[52:55]
	v_mfma_f32_16x16x32_bf16 v[48:51], v[176:179], v[184:187], v[48:51]
	v_mfma_f32_16x16x32_bf16 v[36:39], v[162:165], v[192:195], v[36:39]
	v_mfma_f32_16x16x32_bf16 v[32:35], v[176:179], v[192:195], v[32:35]
	v_mfma_f32_16x16x32_bf16 v[20:23], v[162:165], v[200:203], v[20:23]
	v_mfma_f32_16x16x32_bf16 v[16:19], v[176:179], v[200:203], v[16:19]
	v_mfma_f32_16x16x32_bf16 v[4:7], v[162:165], v[208:211], v[4:7]
	v_mfma_f32_16x16x32_bf16 v[0:3], v[176:179], v[208:211], v[0:3]
	s_barrier
	s_add_u32 s98, s30, 0x2b0000
	s_addc_u32 s99, s31, 0
	ds_read_b128 v[142:145], v169 offset:32768
	ds_read_b128 v[146:149], v169 offset:33792
	ds_read_b128 v[150:153], v169 offset:34816
	ds_read_b128 v[154:157], v169 offset:35840
	ds_read_b128 v[158:161], v170 offset:32768
	ds_read_b128 v[162:165], v170 offset:33792
	ds_read_b128 v[172:175], v170 offset:34816
	ds_read_b128 v[176:179], v170 offset:35840
	ds_read_b128 v[180:183], v171 offset:32768
	ds_read_b128 v[184:187], v171 offset:33792
	ds_read_b128 v[188:191], v171 offset:34816
	ds_read_b128 v[192:195], v171 offset:35840
	ds_read_b128 v[196:199], v171 offset:36864
	ds_read_b128 v[200:203], v171 offset:37888
	ds_read_b128 v[204:207], v171 offset:38912
	ds_read_b128 v[208:211], v171 offset:39936
	s_add_i32 m0, s60, 0x4000
	s_nop 0
	global_load_lds_dwordx4 v128, s[98:99]
	s_add_i32 m0, s60, 0x6000
	s_nop 0
	global_load_lds_dwordx4 v132, s[98:99]
	s_waitcnt vmcnt(8)
	s_waitcnt lgkmcnt(0)
	s_barrier
	v_mfma_f32_16x16x32_bf16 v[124:127], v[142:145], v[180:183], v[124:127]
	v_mfma_f32_16x16x32_bf16 v[120:123], v[150:153], v[180:183], v[120:123]
	v_mfma_f32_16x16x32_bf16 v[108:111], v[142:145], v[188:191], v[108:111]
	v_mfma_f32_16x16x32_bf16 v[104:107], v[150:153], v[188:191], v[104:107]
	v_mfma_f32_16x16x32_bf16 v[92:95], v[142:145], v[196:199], v[92:95]
	v_mfma_f32_16x16x32_bf16 v[88:91], v[150:153], v[196:199], v[88:91]
	v_mfma_f32_16x16x32_bf16 v[76:79], v[142:145], v[204:207], v[76:79]
	v_mfma_f32_16x16x32_bf16 v[72:75], v[150:153], v[204:207], v[72:75]
	v_mfma_f32_16x16x32_bf16 v[124:127], v[146:149], v[184:187], v[124:127]
	v_mfma_f32_16x16x32_bf16 v[120:123], v[154:157], v[184:187], v[120:123]
	v_mfma_f32_16x16x32_bf16 v[108:111], v[146:149], v[192:195], v[108:111]
	v_mfma_f32_16x16x32_bf16 v[104:107], v[154:157], v[192:195], v[104:107]
	v_mfma_f32_16x16x32_bf16 v[92:95], v[146:149], v[200:203], v[92:95]
	v_mfma_f32_16x16x32_bf16 v[88:91], v[154:157], v[200:203], v[88:91]
	v_mfma_f32_16x16x32_bf16 v[76:79], v[146:149], v[208:211], v[76:79]
	v_mfma_f32_16x16x32_bf16 v[72:75], v[154:157], v[208:211], v[72:75]
	v_mfma_f32_16x16x32_bf16 v[116:119], v[158:161], v[180:183], v[116:119]
	v_mfma_f32_16x16x32_bf16 v[112:115], v[172:175], v[180:183], v[112:115]
	v_mfma_f32_16x16x32_bf16 v[100:103], v[158:161], v[188:191], v[100:103]
	v_mfma_f32_16x16x32_bf16 v[96:99], v[172:175], v[188:191], v[96:99]
	v_mfma_f32_16x16x32_bf16 v[84:87], v[158:161], v[196:199], v[84:87]
	v_mfma_f32_16x16x32_bf16 v[80:83], v[172:175], v[196:199], v[80:83]
	v_mfma_f32_16x16x32_bf16 v[68:71], v[158:161], v[204:207], v[68:71]
	v_mfma_f32_16x16x32_bf16 v[64:67], v[172:175], v[204:207], v[64:67]
	v_mfma_f32_16x16x32_bf16 v[116:119], v[162:165], v[184:187], v[116:119]
	v_mfma_f32_16x16x32_bf16 v[112:115], v[176:179], v[184:187], v[112:115]
	v_mfma_f32_16x16x32_bf16 v[100:103], v[162:165], v[192:195], v[100:103]
	v_mfma_f32_16x16x32_bf16 v[96:99], v[176:179], v[192:195], v[96:99]
	v_mfma_f32_16x16x32_bf16 v[84:87], v[162:165], v[200:203], v[84:87]
	v_mfma_f32_16x16x32_bf16 v[80:83], v[176:179], v[200:203], v[80:83]
	v_mfma_f32_16x16x32_bf16 v[68:71], v[162:165], v[208:211], v[68:71]
	v_mfma_f32_16x16x32_bf16 v[64:67], v[176:179], v[208:211], v[64:67]
	s_barrier
	s_add_u32 s100, s52, 0x80
	s_addc_u32 s101, s53, 0
	s_add_u32 s42, s52, 0x2b0080
	s_addc_u32 s43, s53, 0
	s_add_u32 s98, s30, 0x80
	s_addc_u32 s99, s31, 0
	ds_read_b128 v[180:183], v171 offset:49152
	ds_read_b128 v[184:187], v171 offset:50176
	ds_read_b128 v[188:191], v171 offset:51200
	ds_read_b128 v[192:195], v171 offset:52224
	ds_read_b128 v[196:199], v171 offset:53248
	ds_read_b128 v[200:203], v171 offset:54272
	ds_read_b128 v[204:207], v171 offset:55296
	ds_read_b128 v[208:211], v171 offset:56320
	s_add_i32 m0, s60, 0x18000
	s_nop 0
	global_load_lds_dwordx4 v130, s[100:101]
	s_add_i32 m0, s60, 0x1a000
	s_nop 0
	global_load_lds_dwordx4 v134, s[100:101]
	s_add_i32 m0, s60, 0x1c000
	s_nop 0
	global_load_lds_dwordx4 v130, s[42:43]
	s_add_i32 m0, s60, 0x1e000
	s_nop 0
	global_load_lds_dwordx4 v134, s[42:43]
	s_add_i32 m0, s60, 0x8000
	s_nop 0
	global_load_lds_dwordx4 v128, s[98:99]
	s_add_i32 m0, s60, 0xa000
	s_nop 0
	global_load_lds_dwordx4 v132, s[98:99]
	s_waitcnt vmcnt(8)
	s_waitcnt lgkmcnt(0)
	s_barrier
	v_mfma_f32_16x16x32_bf16 v[60:63], v[142:145], v[180:183], v[60:63]
	v_mfma_f32_16x16x32_bf16 v[56:59], v[150:153], v[180:183], v[56:59]
	v_mfma_f32_16x16x32_bf16 v[44:47], v[142:145], v[188:191], v[44:47]
	v_mfma_f32_16x16x32_bf16 v[40:43], v[150:153], v[188:191], v[40:43]
	v_mfma_f32_16x16x32_bf16 v[28:31], v[142:145], v[196:199], v[28:31]
	v_mfma_f32_16x16x32_bf16 v[24:27], v[150:153], v[196:199], v[24:27]
	v_mfma_f32_16x16x32_bf16 v[12:15], v[142:145], v[204:207], v[12:15]
	v_mfma_f32_16x16x32_bf16 v[8:11], v[150:153], v[204:207], v[8:11]
	v_mfma_f32_16x16x32_bf16 v[60:63], v[146:149], v[184:187], v[60:63]
	v_mfma_f32_16x16x32_bf16 v[56:59], v[154:157], v[184:187], v[56:59]
	v_mfma_f32_16x16x32_bf16 v[44:47], v[146:149], v[192:195], v[44:47]
	v_mfma_f32_16x16x32_bf16 v[40:43], v[154:157], v[192:195], v[40:43]
	v_mfma_f32_16x16x32_bf16 v[28:31], v[146:149], v[200:203], v[28:31]
	v_mfma_f32_16x16x32_bf16 v[24:27], v[154:157], v[200:203], v[24:27]
	v_mfma_f32_16x16x32_bf16 v[12:15], v[146:149], v[208:211], v[12:15]
	v_mfma_f32_16x16x32_bf16 v[8:11], v[154:157], v[208:211], v[8:11]
	v_mfma_f32_16x16x32_bf16 v[52:55], v[158:161], v[180:183], v[52:55]
	v_mfma_f32_16x16x32_bf16 v[48:51], v[172:175], v[180:183], v[48:51]
	v_mfma_f32_16x16x32_bf16 v[36:39], v[158:161], v[188:191], v[36:39]
	v_mfma_f32_16x16x32_bf16 v[32:35], v[172:175], v[188:191], v[32:35]
	v_mfma_f32_16x16x32_bf16 v[20:23], v[158:161], v[196:199], v[20:23]
	v_mfma_f32_16x16x32_bf16 v[16:19], v[172:175], v[196:199], v[16:19]
	v_mfma_f32_16x16x32_bf16 v[4:7], v[158:161], v[204:207], v[4:7]
	v_mfma_f32_16x16x32_bf16 v[0:3], v[172:175], v[204:207], v[0:3]
	v_mfma_f32_16x16x32_bf16 v[52:55], v[162:165], v[184:187], v[52:55]
	v_mfma_f32_16x16x32_bf16 v[48:51], v[176:179], v[184:187], v[48:51]
	v_mfma_f32_16x16x32_bf16 v[36:39], v[162:165], v[192:195], v[36:39]
	v_mfma_f32_16x16x32_bf16 v[32:35], v[176:179], v[192:195], v[32:35]
	v_mfma_f32_16x16x32_bf16 v[20:23], v[162:165], v[200:203], v[20:23]
	v_mfma_f32_16x16x32_bf16 v[16:19], v[176:179], v[200:203], v[16:19]
	v_mfma_f32_16x16x32_bf16 v[4:7], v[162:165], v[208:211], v[4:7]
	v_mfma_f32_16x16x32_bf16 v[0:3], v[176:179], v[208:211], v[0:3]
	s_barrier
	s_add_u32 s36, s36, 0x100
	s_addc_u32 s37, s37, 0
	s_cmp_ge_i32 s38, s87
	s_mov_b64 s[44:45], s[46:47]
	s_mov_b32 s30, s38
	s_cbranch_scc0 .LBB0_401
	s_and_b64 vcc, exec, s[12:13]
	s_cbranch_vccz .LBB0_404

.LBB0_576:
	ds_read_b128 v[154:157], v149
	ds_read_b128 v[158:161], v149 offset:1024
	ds_read_b128 v[162:165], v149 offset:2048
	ds_read_b128 v[166:169], v149 offset:3072
	ds_read_b128 v[170:173], v150
	ds_read_b128 v[174:177], v150 offset:1024
	ds_read_b128 v[178:181], v150 offset:2048
	ds_read_b128 v[182:185], v150 offset:3072
	s_add_i32 s42, s30, 2
	s_add_u32 s43, s52, 0xfff00080
	s_addc_u32 s31, s53, -1
	s_cmp_eq_u32 s37, s30
	s_cselect_b32 s30, s15, s43
	s_cselect_b32 s31, s7, s31
	s_cselect_b32 s55, s17, s39
	s_cselect_b32 s54, s35, s38
	v_lshl_add_u64 v[144:145], s[52:53], 0, v[138:139]
	s_add_i32 m0, s9, 0xc000
	ds_read_b128 v[186:189], v151
	ds_read_b128 v[190:193], v151 offset:1024
	ds_read_b128 v[194:197], v151 offset:2048
	ds_read_b128 v[198:201], v151 offset:3072
	ds_read_b128 v[202:205], v151 offset:4096
	ds_read_b128 v[206:209], v151 offset:5120
	ds_read_b128 v[210:213], v151 offset:6144
	ds_read_b128 v[214:217], v151 offset:7168
	global_load_lds_dwordx4 v[144:145], off
	v_lshl_add_u64 v[144:145], s[52:53], 0, v[140:141]
	s_add_i32 m0, s9, 0xe000
	s_nop 0
	global_load_lds_dwordx4 v[144:145], off
	s_waitcnt vmcnt(8)
	s_waitcnt lgkmcnt(0)
	s_barrier
	v_mfma_f32_16x16x32_bf16 v[60:63], v[154:157], v[186:189], v[60:63]
	v_mfma_f32_16x16x32_bf16 v[56:59], v[162:165], v[186:189], v[56:59]
	v_mfma_f32_16x16x32_bf16 v[52:55], v[154:157], v[194:197], v[52:55]
	v_mfma_f32_16x16x32_bf16 v[48:51], v[162:165], v[194:197], v[48:51]
	v_mfma_f32_16x16x32_bf16 v[44:47], v[154:157], v[202:205], v[44:47]
	v_mfma_f32_16x16x32_bf16 v[40:43], v[162:165], v[202:205], v[40:43]
	v_mfma_f32_16x16x32_bf16 v[36:39], v[154:157], v[210:213], v[36:39]
	v_mfma_f32_16x16x32_bf16 v[32:35], v[162:165], v[210:213], v[32:35]
	v_mfma_f32_16x16x32_bf16 v[60:63], v[158:161], v[190:193], v[60:63]
	v_mfma_f32_16x16x32_bf16 v[56:59], v[166:169], v[190:193], v[56:59]
	v_mfma_f32_16x16x32_bf16 v[52:55], v[158:161], v[198:201], v[52:55]
	v_mfma_f32_16x16x32_bf16 v[48:51], v[166:169], v[198:201], v[48:51]
	v_mfma_f32_16x16x32_bf16 v[44:47], v[158:161], v[206:209], v[44:47]
	v_mfma_f32_16x16x32_bf16 v[40:43], v[166:169], v[206:209], v[40:43]
	v_mfma_f32_16x16x32_bf16 v[36:39], v[158:161], v[214:217], v[36:39]
	v_mfma_f32_16x16x32_bf16 v[32:35], v[166:169], v[214:217], v[32:35]
	v_mfma_f32_16x16x32_bf16 v[124:127], v[170:173], v[186:189], v[124:127]
	v_mfma_f32_16x16x32_bf16 v[120:123], v[178:181], v[186:189], v[120:123]
	v_mfma_f32_16x16x32_bf16 v[116:119], v[170:173], v[194:197], v[116:119]
	v_mfma_f32_16x16x32_bf16 v[112:115], v[178:181], v[194:197], v[112:115]
	v_mfma_f32_16x16x32_bf16 v[108:111], v[170:173], v[202:205], v[108:111]
	v_mfma_f32_16x16x32_bf16 v[104:107], v[178:181], v[202:205], v[104:107]
	v_mfma_f32_16x16x32_bf16 v[100:103], v[170:173], v[210:213], v[100:103]
	v_mfma_f32_16x16x32_bf16 v[96:99], v[178:181], v[210:213], v[96:99]
	v_mfma_f32_16x16x32_bf16 v[124:127], v[174:177], v[190:193], v[124:127]
	v_mfma_f32_16x16x32_bf16 v[120:123], v[182:185], v[190:193], v[120:123]
	v_mfma_f32_16x16x32_bf16 v[116:119], v[174:177], v[198:201], v[116:119]
	v_mfma_f32_16x16x32_bf16 v[112:115], v[182:185], v[198:201], v[112:115]
	v_mfma_f32_16x16x32_bf16 v[108:111], v[174:177], v[206:209], v[108:111]
	v_mfma_f32_16x16x32_bf16 v[104:107], v[182:185], v[206:209], v[104:107]
	v_mfma_f32_16x16x32_bf16 v[100:103], v[174:177], v[214:217], v[100:103]
	v_mfma_f32_16x16x32_bf16 v[96:99], v[182:185], v[214:217], v[96:99]
	s_barrier
	s_add_i32 s43, s74, s33
	v_lshl_add_u64 v[144:145], s[54:55], 0, v[130:131]
	s_mov_b32 m0, s43
	ds_read_b128 v[186:189], v151 offset:16384
	ds_read_b128 v[190:193], v151 offset:17408
	ds_read_b128 v[194:197], v151 offset:18432
	ds_read_b128 v[198:201], v151 offset:19456
	ds_read_b128 v[202:205], v151 offset:20480
	ds_read_b128 v[206:209], v151 offset:21504
	ds_read_b128 v[210:213], v151 offset:22528
	ds_read_b128 v[214:217], v151 offset:23552
	global_load_lds_dwordx4 v[144:145], off
	s_add_i32 m0, s43, 0x2000
	s_add_u32 s48, s54, 0x100000
	v_lshl_add_u64 v[218:219], s[54:55], 0, v[134:135]
	s_addc_u32 s49, s55, 0
	s_add_i32 s43, s75, s33
	global_load_lds_dwordx4 v[218:219], off
	v_lshl_add_u64 v[220:221], s[48:49], 0, v[130:131]
	s_mov_b32 m0, s43
	v_lshl_add_u64 v[222:223], s[30:31], 0, v[132:133]
	global_load_lds_dwordx4 v[220:221], off
	v_lshl_add_u64 v[220:221], s[48:49], 0, v[134:135]
	s_add_i32 m0, s43, 0x2000
	s_nop 0
	global_load_lds_dwordx4 v[220:221], off
	v_lshl_add_u64 v[220:221], s[30:31], 0, v[128:129]
	s_mov_b32 m0, s9
	s_nop 0
	global_load_lds_dwordx4 v[220:221], off
	s_mov_b32 m0, s58
	s_nop 0
	global_load_lds_dwordx4 v[222:223], off
	s_waitcnt vmcnt(8)
	s_waitcnt lgkmcnt(0)
	s_barrier
	v_mfma_f32_16x16x32_bf16 v[28:31], v[154:157], v[186:189], v[28:31]
	v_mfma_f32_16x16x32_bf16 v[24:27], v[162:165], v[186:189], v[24:27]
	v_mfma_f32_16x16x32_bf16 v[20:23], v[154:157], v[194:197], v[20:23]
	v_mfma_f32_16x16x32_bf16 v[16:19], v[162:165], v[194:197], v[16:19]
	v_mfma_f32_16x16x32_bf16 v[12:15], v[154:157], v[202:205], v[12:15]
	v_mfma_f32_16x16x32_bf16 v[8:11], v[162:165], v[202:205], v[8:11]
	v_mfma_f32_16x16x32_bf16 v[4:7], v[154:157], v[210:213], v[4:7]
	v_mfma_f32_16x16x32_bf16 v[0:3], v[162:165], v[210:213], v[0:3]
	v_mfma_f32_16x16x32_bf16 v[28:31], v[158:161], v[190:193], v[28:31]
	v_mfma_f32_16x16x32_bf16 v[24:27], v[166:169], v[190:193], v[24:27]
	v_mfma_f32_16x16x32_bf16 v[20:23], v[158:161], v[198:201], v[20:23]
	v_mfma_f32_16x16x32_bf16 v[16:19], v[166:169], v[198:201], v[16:19]
	v_mfma_f32_16x16x32_bf16 v[12:15], v[158:161], v[206:209], v[12:15]
	v_mfma_f32_16x16x32_bf16 v[8:11], v[166:169], v[206:209], v[8:11]
	v_mfma_f32_16x16x32_bf16 v[4:7], v[158:161], v[214:217], v[4:7]
	v_mfma_f32_16x16x32_bf16 v[0:3], v[166:169], v[214:217], v[0:3]
	v_mfma_f32_16x16x32_bf16 v[92:95], v[170:173], v[186:189], v[92:95]
	v_mfma_f32_16x16x32_bf16 v[88:91], v[178:181], v[186:189], v[88:91]
	v_mfma_f32_16x16x32_bf16 v[84:87], v[170:173], v[194:197], v[84:87]
	v_mfma_f32_16x16x32_bf16 v[80:83], v[178:181], v[194:197], v[80:83]
	v_mfma_f32_16x16x32_bf16 v[76:79], v[170:173], v[202:205], v[76:79]
	v_mfma_f32_16x16x32_bf16 v[72:75], v[178:181], v[202:205], v[72:75]
	v_mfma_f32_16x16x32_bf16 v[68:71], v[170:173], v[210:213], v[68:71]
	v_mfma_f32_16x16x32_bf16 v[64:67], v[178:181], v[210:213], v[64:67]
	v_mfma_f32_16x16x32_bf16 v[92:95], v[174:177], v[190:193], v[92:95]
	v_mfma_f32_16x16x32_bf16 v[88:91], v[182:185], v[190:193], v[88:91]
	v_mfma_f32_16x16x32_bf16 v[84:87], v[174:177], v[198:201], v[84:87]
	v_mfma_f32_16x16x32_bf16 v[80:83], v[182:185], v[198:201], v[80:83]
	v_mfma_f32_16x16x32_bf16 v[76:79], v[174:177], v[206:209], v[76:79]
	v_mfma_f32_16x16x32_bf16 v[72:75], v[182:185], v[206:209], v[72:75]
	v_mfma_f32_16x16x32_bf16 v[68:71], v[174:177], v[214:217], v[68:71]
	v_mfma_f32_16x16x32_bf16 v[64:67], v[182:185], v[214:217], v[64:67]
	s_barrier
	s_add_i32 s43, 0, 0x18000
	v_add_u32_e32 v153, s43, v147
	s_add_i32 s48, 0, 0x1c000
	ds_read_b128 v[154:157], v153
	ds_read_b128 v[158:161], v153 offset:1024
	ds_read_b128 v[162:165], v153 offset:2048
	ds_read_b128 v[166:169], v153 offset:3072
	v_add_u32_e32 v153, s48, v147
	ds_read_b128 v[170:173], v153
	ds_read_b128 v[174:177], v153 offset:1024
	ds_read_b128 v[178:181], v153 offset:2048
	ds_read_b128 v[182:185], v153 offset:3072
	s_add_u32 s30, s30, 0x100000
	s_addc_u32 s31, s31, 0
	s_mov_b32 m0, s59
	v_lshl_add_u64 v[224:225], s[30:31], 0, v[128:129]
	ds_read_b128 v[186:189], v151 offset:32768
	ds_read_b128 v[190:193], v151 offset:33792
	ds_read_b128 v[194:197], v151 offset:34816
	ds_read_b128 v[198:201], v151 offset:35840
	ds_read_b128 v[202:205], v151 offset:36864
	ds_read_b128 v[206:209], v151 offset:37888
	ds_read_b128 v[210:213], v151 offset:38912
	ds_read_b128 v[214:217], v151 offset:39936
	global_load_lds_dwordx4 v[224:225], off
	v_lshl_add_u64 v[224:225], s[30:31], 0, v[132:133]
	s_mov_b32 m0, s60
	s_nop 0
	global_load_lds_dwordx4 v[224:225], off
	s_waitcnt vmcnt(8)
	s_waitcnt lgkmcnt(0)
	s_barrier
	v_mfma_f32_16x16x32_bf16 v[60:63], v[154:157], v[186:189], v[60:63]
	v_mfma_f32_16x16x32_bf16 v[56:59], v[162:165], v[186:189], v[56:59]
	v_mfma_f32_16x16x32_bf16 v[52:55], v[154:157], v[194:197], v[52:55]
	v_mfma_f32_16x16x32_bf16 v[48:51], v[162:165], v[194:197], v[48:51]
	v_mfma_f32_16x16x32_bf16 v[44:47], v[154:157], v[202:205], v[44:47]
	v_mfma_f32_16x16x32_bf16 v[40:43], v[162:165], v[202:205], v[40:43]
	v_mfma_f32_16x16x32_bf16 v[36:39], v[154:157], v[210:213], v[36:39]
	v_mfma_f32_16x16x32_bf16 v[32:35], v[162:165], v[210:213], v[32:35]
	v_mfma_f32_16x16x32_bf16 v[60:63], v[158:161], v[190:193], v[60:63]
	v_mfma_f32_16x16x32_bf16 v[56:59], v[166:169], v[190:193], v[56:59]
	v_mfma_f32_16x16x32_bf16 v[52:55], v[158:161], v[198:201], v[52:55]
	v_mfma_f32_16x16x32_bf16 v[48:51], v[166:169], v[198:201], v[48:51]
	v_mfma_f32_16x16x32_bf16 v[44:47], v[158:161], v[206:209], v[44:47]
	v_mfma_f32_16x16x32_bf16 v[40:43], v[166:169], v[206:209], v[40:43]
	v_mfma_f32_16x16x32_bf16 v[36:39], v[158:161], v[214:217], v[36:39]
	v_mfma_f32_16x16x32_bf16 v[32:35], v[166:169], v[214:217], v[32:35]
	v_mfma_f32_16x16x32_bf16 v[124:127], v[170:173], v[186:189], v[124:127]
	v_mfma_f32_16x16x32_bf16 v[120:123], v[178:181], v[186:189], v[120:123]
	v_mfma_f32_16x16x32_bf16 v[116:119], v[170:173], v[194:197], v[116:119]
	v_mfma_f32_16x16x32_bf16 v[112:115], v[178:181], v[194:197], v[112:115]
	v_mfma_f32_16x16x32_bf16 v[108:111], v[170:173], v[202:205], v[108:111]
	v_mfma_f32_16x16x32_bf16 v[104:107], v[178:181], v[202:205], v[104:107]
	v_mfma_f32_16x16x32_bf16 v[100:103], v[170:173], v[210:213], v[100:103]
	v_mfma_f32_16x16x32_bf16 v[96:99], v[178:181], v[210:213], v[96:99]
	v_mfma_f32_16x16x32_bf16 v[124:127], v[174:177], v[190:193], v[124:127]
	v_mfma_f32_16x16x32_bf16 v[120:123], v[182:185], v[190:193], v[120:123]
	v_mfma_f32_16x16x32_bf16 v[116:119], v[174:177], v[198:201], v[116:119]
	v_mfma_f32_16x16x32_bf16 v[112:115], v[182:185], v[198:201], v[112:115]
	v_mfma_f32_16x16x32_bf16 v[108:111], v[174:177], v[206:209], v[108:111]
	v_mfma_f32_16x16x32_bf16 v[104:107], v[182:185], v[206:209], v[104:107]
	v_mfma_f32_16x16x32_bf16 v[100:103], v[174:177], v[214:217], v[100:103]
	v_mfma_f32_16x16x32_bf16 v[96:99], v[182:185], v[214:217], v[96:99]
	s_barrier
	s_add_i32 s30, s43, s33
	v_lshl_add_u64 v[144:145], v[144:145], 0, s[4:5]
	s_mov_b32 m0, s30
	ds_read_b128 v[186:189], v151 offset:49152
	ds_read_b128 v[190:193], v151 offset:50176
	ds_read_b128 v[194:197], v151 offset:51200
	ds_read_b128 v[198:201], v151 offset:52224
	ds_read_b128 v[202:205], v151 offset:53248
	ds_read_b128 v[206:209], v151 offset:54272
	ds_read_b128 v[210:213], v151 offset:55296
	ds_read_b128 v[214:217], v151 offset:56320
	global_load_lds_dwordx4 v[144:145], off
	s_add_i32 m0, s30, 0x2000
	s_add_u32 s30, s54, 0x100080
	v_lshl_add_u64 v[144:145], v[218:219], 0, s[4:5]
	s_addc_u32 s31, s55, 0
	s_add_i32 s43, s48, s33
	global_load_lds_dwordx4 v[144:145], off
	v_lshl_add_u64 v[144:145], s[30:31], 0, v[130:131]
	s_mov_b32 m0, s43
	s_nop 0
	global_load_lds_dwordx4 v[144:145], off
	v_lshl_add_u64 v[144:145], s[30:31], 0, v[134:135]
	s_add_i32 m0, s43, 0x2000
	s_nop 0
	global_load_lds_dwordx4 v[144:145], off
	v_lshl_add_u64 v[144:145], v[220:221], 0, s[4:5]
	s_mov_b32 m0, s70
	s_nop 0
	global_load_lds_dwordx4 v[144:145], off
	v_lshl_add_u64 v[144:145], v[222:223], 0, s[4:5]
	s_mov_b32 m0, s71
	s_nop 0
	global_load_lds_dwordx4 v[144:145], off
	s_waitcnt vmcnt(8)
	s_waitcnt lgkmcnt(0)
	s_barrier
	v_mfma_f32_16x16x32_bf16 v[28:31], v[154:157], v[186:189], v[28:31]
	v_mfma_f32_16x16x32_bf16 v[24:27], v[162:165], v[186:189], v[24:27]
	v_mfma_f32_16x16x32_bf16 v[20:23], v[154:157], v[194:197], v[20:23]
	v_mfma_f32_16x16x32_bf16 v[16:19], v[162:165], v[194:197], v[16:19]
	v_mfma_f32_16x16x32_bf16 v[12:15], v[154:157], v[202:205], v[12:15]
	v_mfma_f32_16x16x32_bf16 v[8:11], v[162:165], v[202:205], v[8:11]
	v_mfma_f32_16x16x32_bf16 v[4:7], v[154:157], v[210:213], v[4:7]
	v_mfma_f32_16x16x32_bf16 v[0:3], v[162:165], v[210:213], v[0:3]
	v_mfma_f32_16x16x32_bf16 v[28:31], v[158:161], v[190:193], v[28:31]
	v_mfma_f32_16x16x32_bf16 v[24:27], v[166:169], v[190:193], v[24:27]
	v_mfma_f32_16x16x32_bf16 v[20:23], v[158:161], v[198:201], v[20:23]
	v_mfma_f32_16x16x32_bf16 v[16:19], v[166:169], v[198:201], v[16:19]
	v_mfma_f32_16x16x32_bf16 v[12:15], v[158:161], v[206:209], v[12:15]
	v_mfma_f32_16x16x32_bf16 v[8:11], v[166:169], v[206:209], v[8:11]
	v_mfma_f32_16x16x32_bf16 v[4:7], v[158:161], v[214:217], v[4:7]
	v_mfma_f32_16x16x32_bf16 v[0:3], v[166:169], v[214:217], v[0:3]
	v_mfma_f32_16x16x32_bf16 v[92:95], v[170:173], v[186:189], v[92:95]
	v_mfma_f32_16x16x32_bf16 v[88:91], v[178:181], v[186:189], v[88:91]
	v_mfma_f32_16x16x32_bf16 v[84:87], v[170:173], v[194:197], v[84:87]
	v_mfma_f32_16x16x32_bf16 v[80:83], v[178:181], v[194:197], v[80:83]
	v_mfma_f32_16x16x32_bf16 v[76:79], v[170:173], v[202:205], v[76:79]
	v_mfma_f32_16x16x32_bf16 v[72:75], v[178:181], v[202:205], v[72:75]
	v_mfma_f32_16x16x32_bf16 v[68:71], v[170:173], v[210:213], v[68:71]
	v_mfma_f32_16x16x32_bf16 v[64:67], v[178:181], v[210:213], v[64:67]
	v_mfma_f32_16x16x32_bf16 v[92:95], v[174:177], v[190:193], v[92:95]
	v_mfma_f32_16x16x32_bf16 v[88:91], v[182:185], v[190:193], v[88:91]
	v_mfma_f32_16x16x32_bf16 v[84:87], v[174:177], v[198:201], v[84:87]
	v_mfma_f32_16x16x32_bf16 v[80:83], v[182:185], v[198:201], v[80:83]
	v_mfma_f32_16x16x32_bf16 v[76:79], v[174:177], v[206:209], v[76:79]
	v_mfma_f32_16x16x32_bf16 v[72:75], v[182:185], v[206:209], v[72:75]
	v_mfma_f32_16x16x32_bf16 v[68:71], v[174:177], v[214:217], v[68:71]
	v_mfma_f32_16x16x32_bf16 v[64:67], v[182:185], v[214:217], v[64:67]
	s_barrier
	s_add_u32 s52, s52, 0x100
	s_addc_u32 s53, s53, 0
	s_add_u32 s38, s38, 0x100
	s_addc_u32 s39, s39, 0
	s_cmp_ge_i32 s42, s36
	s_mov_b32 s30, s42
	s_cbranch_scc0 .LBB0_576
	s_and_b64 vcc, exec, s[10:11]
	s_cbranch_vccz .LBB0_581

.LBB0_738:
	ds_read_b128 v[182:185], v129
	ds_read_b128 v[186:189], v129 offset:1024
	ds_read_b128 v[190:193], v129 offset:2048
	ds_read_b128 v[194:197], v129 offset:3072
	ds_read_b128 v[198:201], v178
	ds_read_b128 v[202:205], v178 offset:1024
	ds_read_b128 v[206:209], v178 offset:2048
	ds_read_b128 v[210:213], v178 offset:3072
	s_add_u32 s30, s44, 0xfffc0080
	s_addc_u32 s31, s45, -1
	s_cmp_eq_u32 s50, 12
	s_cselect_b32 s31, s36, s31
	s_cselect_b32 s30, s37, s30
	s_cselect_b32 s47, s35, s49
	s_cselect_b32 s46, s39, s48
	v_lshl_add_u64 v[154:155], s[44:45], 0, v[146:147]
	s_add_i32 m0, s54, 0xc000
	ds_read_b128 v[214:217], v179
	ds_read_b128 v[218:221], v179 offset:1024
	ds_read_b128 v[222:225], v179 offset:2048
	ds_read_b128 v[226:229], v179 offset:3072
	ds_read_b128 v[230:233], v179 offset:4096
	ds_read_b128 v[234:237], v179 offset:5120
	ds_read_b128 v[238:241], v179 offset:6144
	ds_read_b128 v[242:245], v179 offset:7168
	global_load_lds_dwordx4 v[154:155], off
	v_lshl_add_u64 v[154:155], s[44:45], 0, v[148:149]
	s_add_i32 m0, s54, 0xe000
	s_nop 0
	global_load_lds_dwordx4 v[154:155], off
	s_waitcnt vmcnt(8)
	s_waitcnt lgkmcnt(0)
	s_barrier
	v_mfma_f32_16x16x32_bf16 v[124:127], v[182:185], v[214:217], v[124:127]
	v_mfma_f32_16x16x32_bf16 v[120:123], v[190:193], v[214:217], v[120:123]
	v_mfma_f32_16x16x32_bf16 v[116:119], v[182:185], v[222:225], v[116:119]
	v_mfma_f32_16x16x32_bf16 v[108:111], v[190:193], v[222:225], v[108:111]
	v_mfma_f32_16x16x32_bf16 v[100:103], v[182:185], v[230:233], v[100:103]
	v_mfma_f32_16x16x32_bf16 v[92:95], v[190:193], v[230:233], v[92:95]
	v_mfma_f32_16x16x32_bf16 v[84:87], v[182:185], v[238:241], v[84:87]
	v_mfma_f32_16x16x32_bf16 v[76:79], v[190:193], v[238:241], v[76:79]
	v_mfma_f32_16x16x32_bf16 v[124:127], v[186:189], v[218:221], v[124:127]
	v_mfma_f32_16x16x32_bf16 v[120:123], v[194:197], v[218:221], v[120:123]
	v_mfma_f32_16x16x32_bf16 v[116:119], v[186:189], v[226:229], v[116:119]
	v_mfma_f32_16x16x32_bf16 v[108:111], v[194:197], v[226:229], v[108:111]
	v_mfma_f32_16x16x32_bf16 v[100:103], v[186:189], v[234:237], v[100:103]
	v_mfma_f32_16x16x32_bf16 v[92:95], v[194:197], v[234:237], v[92:95]
	v_mfma_f32_16x16x32_bf16 v[84:87], v[186:189], v[242:245], v[84:87]
	v_mfma_f32_16x16x32_bf16 v[76:79], v[194:197], v[242:245], v[76:79]
	v_mfma_f32_16x16x32_bf16 v[112:115], v[198:201], v[214:217], v[112:115]
	v_mfma_f32_16x16x32_bf16 v[104:107], v[206:209], v[214:217], v[104:107]
	v_mfma_f32_16x16x32_bf16 v[96:99], v[198:201], v[222:225], v[96:99]
	v_mfma_f32_16x16x32_bf16 v[88:91], v[206:209], v[222:225], v[88:91]
	v_mfma_f32_16x16x32_bf16 v[80:83], v[198:201], v[230:233], v[80:83]
	v_mfma_f32_16x16x32_bf16 v[72:75], v[206:209], v[230:233], v[72:75]
	v_mfma_f32_16x16x32_bf16 v[68:71], v[198:201], v[238:241], v[68:71]
	v_mfma_f32_16x16x32_bf16 v[64:67], v[206:209], v[238:241], v[64:67]
	v_mfma_f32_16x16x32_bf16 v[112:115], v[202:205], v[218:221], v[112:115]
	v_mfma_f32_16x16x32_bf16 v[104:107], v[210:213], v[218:221], v[104:107]
	v_mfma_f32_16x16x32_bf16 v[96:99], v[202:205], v[226:229], v[96:99]
	v_mfma_f32_16x16x32_bf16 v[88:91], v[210:213], v[226:229], v[88:91]
	v_mfma_f32_16x16x32_bf16 v[80:83], v[202:205], v[234:237], v[80:83]
	v_mfma_f32_16x16x32_bf16 v[72:75], v[210:213], v[234:237], v[72:75]
	v_mfma_f32_16x16x32_bf16 v[68:71], v[202:205], v[242:245], v[68:71]
	v_mfma_f32_16x16x32_bf16 v[64:67], v[210:213], v[242:245], v[64:67]
	s_barrier
	s_add_i32 s51, s62, s15
	v_lshl_add_u64 v[154:155], s[46:47], 0, v[136:137]
	s_mov_b32 m0, s51
	ds_read_b128 v[214:217], v179 offset:16384
	ds_read_b128 v[218:221], v179 offset:17408
	ds_read_b128 v[222:225], v179 offset:18432
	ds_read_b128 v[226:229], v179 offset:19456
	ds_read_b128 v[230:233], v179 offset:20480
	ds_read_b128 v[234:237], v179 offset:21504
	ds_read_b128 v[238:241], v179 offset:22528
	ds_read_b128 v[242:245], v179 offset:23552
	global_load_lds_dwordx4 v[154:155], off
	s_add_i32 m0, s51, 0x2000
	s_add_u32 s70, s46, 0x40000
	v_lshl_add_u64 v[246:247], s[46:47], 0, v[132:133]
	s_addc_u32 s71, s47, 0
	s_add_i32 s51, s63, s15
	global_load_lds_dwordx4 v[246:247], off
	v_lshl_add_u64 v[248:249], s[70:71], 0, v[136:137]
	s_mov_b32 m0, s51
	v_lshl_add_u64 v[250:251], s[30:31], 0, v[134:135]
	global_load_lds_dwordx4 v[248:249], off
	v_lshl_add_u64 v[248:249], s[70:71], 0, v[132:133]
	s_add_i32 m0, s51, 0x2000
	s_nop 0
	global_load_lds_dwordx4 v[248:249], off
	v_lshl_add_u64 v[248:249], s[30:31], 0, v[138:139]
	s_mov_b32 m0, s54
	s_nop 0
	global_load_lds_dwordx4 v[248:249], off
	s_mov_b32 m0, s55
	s_nop 0
	global_load_lds_dwordx4 v[250:251], off
	s_waitcnt vmcnt(8)
	s_waitcnt lgkmcnt(0)
	s_barrier
	v_mfma_f32_16x16x32_bf16 v[60:63], v[182:185], v[214:217], v[60:63]
	v_mfma_f32_16x16x32_bf16 v[56:59], v[190:193], v[214:217], v[56:59]
	v_mfma_f32_16x16x32_bf16 v[52:55], v[182:185], v[222:225], v[52:55]
	v_mfma_f32_16x16x32_bf16 v[44:47], v[190:193], v[222:225], v[44:47]
	v_mfma_f32_16x16x32_bf16 v[36:39], v[182:185], v[230:233], v[36:39]
	v_mfma_f32_16x16x32_bf16 v[28:31], v[190:193], v[230:233], v[28:31]
	v_mfma_f32_16x16x32_bf16 v[20:23], v[182:185], v[238:241], v[20:23]
	v_mfma_f32_16x16x32_bf16 v[12:15], v[190:193], v[238:241], v[12:15]
	v_mfma_f32_16x16x32_bf16 v[60:63], v[186:189], v[218:221], v[60:63]
	v_mfma_f32_16x16x32_bf16 v[56:59], v[194:197], v[218:221], v[56:59]
	v_mfma_f32_16x16x32_bf16 v[52:55], v[186:189], v[226:229], v[52:55]
	v_mfma_f32_16x16x32_bf16 v[44:47], v[194:197], v[226:229], v[44:47]
	v_mfma_f32_16x16x32_bf16 v[36:39], v[186:189], v[234:237], v[36:39]
	v_mfma_f32_16x16x32_bf16 v[28:31], v[194:197], v[234:237], v[28:31]
	v_mfma_f32_16x16x32_bf16 v[20:23], v[186:189], v[242:245], v[20:23]
	v_mfma_f32_16x16x32_bf16 v[12:15], v[194:197], v[242:245], v[12:15]
	v_mfma_f32_16x16x32_bf16 v[48:51], v[198:201], v[214:217], v[48:51]
	v_mfma_f32_16x16x32_bf16 v[40:43], v[206:209], v[214:217], v[40:43]
	v_mfma_f32_16x16x32_bf16 v[32:35], v[198:201], v[222:225], v[32:35]
	v_mfma_f32_16x16x32_bf16 v[24:27], v[206:209], v[222:225], v[24:27]
	v_mfma_f32_16x16x32_bf16 v[16:19], v[198:201], v[230:233], v[16:19]
	v_mfma_f32_16x16x32_bf16 v[8:11], v[206:209], v[230:233], v[8:11]
	v_mfma_f32_16x16x32_bf16 v[4:7], v[198:201], v[238:241], v[4:7]
	v_mfma_f32_16x16x32_bf16 v[0:3], v[206:209], v[238:241], v[0:3]
	v_mfma_f32_16x16x32_bf16 v[48:51], v[202:205], v[218:221], v[48:51]
	v_mfma_f32_16x16x32_bf16 v[40:43], v[210:213], v[218:221], v[40:43]
	v_mfma_f32_16x16x32_bf16 v[32:35], v[202:205], v[226:229], v[32:35]
	v_mfma_f32_16x16x32_bf16 v[24:27], v[210:213], v[226:229], v[24:27]
	v_mfma_f32_16x16x32_bf16 v[16:19], v[202:205], v[234:237], v[16:19]
	v_mfma_f32_16x16x32_bf16 v[8:11], v[210:213], v[234:237], v[8:11]
	v_mfma_f32_16x16x32_bf16 v[4:7], v[202:205], v[242:245], v[4:7]
	v_mfma_f32_16x16x32_bf16 v[0:3], v[210:213], v[242:245], v[0:3]
	s_barrier
	s_add_i32 s51, 0, 0x18000
	v_add_u32_e32 v166, s51, v176
	s_add_i32 s70, 0, 0x1c000
	ds_read_b128 v[182:185], v166
	ds_read_b128 v[186:189], v166 offset:1024
	ds_read_b128 v[190:193], v166 offset:2048
	ds_read_b128 v[194:197], v166 offset:3072
	v_add_u32_e32 v166, s70, v176
	ds_read_b128 v[198:201], v166
	ds_read_b128 v[202:205], v166 offset:1024
	ds_read_b128 v[206:209], v166 offset:2048
	ds_read_b128 v[210:213], v166 offset:3072
	s_add_u32 s30, s30, 0x40000
	s_addc_u32 s31, s31, 0
	s_mov_b32 m0, s56
	v_lshl_add_u64 v[166:167], s[30:31], 0, v[138:139]
	ds_read_b128 v[214:217], v179 offset:32768
	ds_read_b128 v[218:221], v179 offset:33792
	ds_read_b128 v[222:225], v179 offset:34816
	ds_read_b128 v[226:229], v179 offset:35840
	ds_read_b128 v[230:233], v179 offset:36864
	ds_read_b128 v[234:237], v179 offset:37888
	ds_read_b128 v[238:241], v179 offset:38912
	ds_read_b128 v[242:245], v179 offset:39936
	global_load_lds_dwordx4 v[166:167], off
	v_lshl_add_u64 v[166:167], s[30:31], 0, v[134:135]
	s_mov_b32 m0, s57
	s_nop 0
	global_load_lds_dwordx4 v[166:167], off
	s_waitcnt vmcnt(8)
	s_waitcnt lgkmcnt(0)
	s_barrier
	v_mfma_f32_16x16x32_bf16 v[124:127], v[182:185], v[214:217], v[124:127]
	v_mfma_f32_16x16x32_bf16 v[120:123], v[190:193], v[214:217], v[120:123]
	v_mfma_f32_16x16x32_bf16 v[116:119], v[182:185], v[222:225], v[116:119]
	v_mfma_f32_16x16x32_bf16 v[108:111], v[190:193], v[222:225], v[108:111]
	v_mfma_f32_16x16x32_bf16 v[100:103], v[182:185], v[230:233], v[100:103]
	v_mfma_f32_16x16x32_bf16 v[92:95], v[190:193], v[230:233], v[92:95]
	v_mfma_f32_16x16x32_bf16 v[84:87], v[182:185], v[238:241], v[84:87]
	v_mfma_f32_16x16x32_bf16 v[76:79], v[190:193], v[238:241], v[76:79]
	v_mfma_f32_16x16x32_bf16 v[124:127], v[186:189], v[218:221], v[124:127]
	v_mfma_f32_16x16x32_bf16 v[120:123], v[194:197], v[218:221], v[120:123]
	v_mfma_f32_16x16x32_bf16 v[116:119], v[186:189], v[226:229], v[116:119]
	v_mfma_f32_16x16x32_bf16 v[108:111], v[194:197], v[226:229], v[108:111]
	v_mfma_f32_16x16x32_bf16 v[100:103], v[186:189], v[234:237], v[100:103]
	v_mfma_f32_16x16x32_bf16 v[92:95], v[194:197], v[234:237], v[92:95]
	v_mfma_f32_16x16x32_bf16 v[84:87], v[186:189], v[242:245], v[84:87]
	v_mfma_f32_16x16x32_bf16 v[76:79], v[194:197], v[242:245], v[76:79]
	v_mfma_f32_16x16x32_bf16 v[112:115], v[198:201], v[214:217], v[112:115]
	v_mfma_f32_16x16x32_bf16 v[104:107], v[206:209], v[214:217], v[104:107]
	v_mfma_f32_16x16x32_bf16 v[96:99], v[198:201], v[222:225], v[96:99]
	v_mfma_f32_16x16x32_bf16 v[88:91], v[206:209], v[222:225], v[88:91]
	v_mfma_f32_16x16x32_bf16 v[80:83], v[198:201], v[230:233], v[80:83]
	v_mfma_f32_16x16x32_bf16 v[72:75], v[206:209], v[230:233], v[72:75]
	v_mfma_f32_16x16x32_bf16 v[68:71], v[198:201], v[238:241], v[68:71]
	v_mfma_f32_16x16x32_bf16 v[64:67], v[206:209], v[238:241], v[64:67]
	v_mfma_f32_16x16x32_bf16 v[112:115], v[202:205], v[218:221], v[112:115]
	v_mfma_f32_16x16x32_bf16 v[104:107], v[210:213], v[218:221], v[104:107]
	v_mfma_f32_16x16x32_bf16 v[96:99], v[202:205], v[226:229], v[96:99]
	v_mfma_f32_16x16x32_bf16 v[88:91], v[210:213], v[226:229], v[88:91]
	v_mfma_f32_16x16x32_bf16 v[80:83], v[202:205], v[234:237], v[80:83]
	v_mfma_f32_16x16x32_bf16 v[72:75], v[210:213], v[234:237], v[72:75]
	v_mfma_f32_16x16x32_bf16 v[68:71], v[202:205], v[242:245], v[68:71]
	v_mfma_f32_16x16x32_bf16 v[64:67], v[210:213], v[242:245], v[64:67]
	s_barrier
	s_add_i32 s30, s51, s15
	v_lshl_add_u64 v[154:155], v[154:155], 0, s[6:7]
	s_mov_b32 m0, s30
	ds_read_b128 v[214:217], v179 offset:49152
	ds_read_b128 v[218:221], v179 offset:50176
	ds_read_b128 v[222:225], v179 offset:51200
	ds_read_b128 v[226:229], v179 offset:52224
	ds_read_b128 v[230:233], v179 offset:53248
	ds_read_b128 v[234:237], v179 offset:54272
	ds_read_b128 v[238:241], v179 offset:55296
	ds_read_b128 v[242:245], v179 offset:56320
	global_load_lds_dwordx4 v[154:155], off
	s_add_i32 m0, s30, 0x2000
	s_add_u32 s30, s46, 0x40080
	v_lshl_add_u64 v[154:155], v[246:247], 0, s[6:7]
	s_addc_u32 s31, s47, 0
	s_add_i32 s46, s70, s15
	global_load_lds_dwordx4 v[154:155], off
	v_lshl_add_u64 v[154:155], s[30:31], 0, v[136:137]
	s_mov_b32 m0, s46
	s_nop 0
	global_load_lds_dwordx4 v[154:155], off
	v_lshl_add_u64 v[154:155], s[30:31], 0, v[132:133]
	s_add_i32 m0, s46, 0x2000
	s_nop 0
	global_load_lds_dwordx4 v[154:155], off
	v_lshl_add_u64 v[154:155], v[248:249], 0, s[6:7]
	s_mov_b32 m0, s59
	s_nop 0
	global_load_lds_dwordx4 v[154:155], off
	v_lshl_add_u64 v[154:155], v[250:251], 0, s[6:7]
	s_mov_b32 m0, s60
	s_nop 0
	global_load_lds_dwordx4 v[154:155], off
	s_waitcnt vmcnt(8)
	s_waitcnt lgkmcnt(0)
	s_barrier
	v_mfma_f32_16x16x32_bf16 v[60:63], v[182:185], v[214:217], v[60:63]
	v_mfma_f32_16x16x32_bf16 v[56:59], v[190:193], v[214:217], v[56:59]
	v_mfma_f32_16x16x32_bf16 v[52:55], v[182:185], v[222:225], v[52:55]
	v_mfma_f32_16x16x32_bf16 v[44:47], v[190:193], v[222:225], v[44:47]
	v_mfma_f32_16x16x32_bf16 v[36:39], v[182:185], v[230:233], v[36:39]
	v_mfma_f32_16x16x32_bf16 v[28:31], v[190:193], v[230:233], v[28:31]
	v_mfma_f32_16x16x32_bf16 v[20:23], v[182:185], v[238:241], v[20:23]
	v_mfma_f32_16x16x32_bf16 v[12:15], v[190:193], v[238:241], v[12:15]
	v_mfma_f32_16x16x32_bf16 v[60:63], v[186:189], v[218:221], v[60:63]
	v_mfma_f32_16x16x32_bf16 v[56:59], v[194:197], v[218:221], v[56:59]
	v_mfma_f32_16x16x32_bf16 v[52:55], v[186:189], v[226:229], v[52:55]
	v_mfma_f32_16x16x32_bf16 v[44:47], v[194:197], v[226:229], v[44:47]
	v_mfma_f32_16x16x32_bf16 v[36:39], v[186:189], v[234:237], v[36:39]
	v_mfma_f32_16x16x32_bf16 v[28:31], v[194:197], v[234:237], v[28:31]
	v_mfma_f32_16x16x32_bf16 v[20:23], v[186:189], v[242:245], v[20:23]
	v_mfma_f32_16x16x32_bf16 v[12:15], v[194:197], v[242:245], v[12:15]
	v_mfma_f32_16x16x32_bf16 v[48:51], v[198:201], v[214:217], v[48:51]
	v_mfma_f32_16x16x32_bf16 v[40:43], v[206:209], v[214:217], v[40:43]
	v_mfma_f32_16x16x32_bf16 v[32:35], v[198:201], v[222:225], v[32:35]
	v_mfma_f32_16x16x32_bf16 v[24:27], v[206:209], v[222:225], v[24:27]
	v_mfma_f32_16x16x32_bf16 v[16:19], v[198:201], v[230:233], v[16:19]
	v_mfma_f32_16x16x32_bf16 v[8:11], v[206:209], v[230:233], v[8:11]
	v_mfma_f32_16x16x32_bf16 v[4:7], v[198:201], v[238:241], v[4:7]
	v_mfma_f32_16x16x32_bf16 v[0:3], v[206:209], v[238:241], v[0:3]
	v_mfma_f32_16x16x32_bf16 v[48:51], v[202:205], v[218:221], v[48:51]
	v_mfma_f32_16x16x32_bf16 v[40:43], v[210:213], v[218:221], v[40:43]
	v_mfma_f32_16x16x32_bf16 v[32:35], v[202:205], v[226:229], v[32:35]
	v_mfma_f32_16x16x32_bf16 v[24:27], v[210:213], v[226:229], v[24:27]
	v_mfma_f32_16x16x32_bf16 v[16:19], v[202:205], v[234:237], v[16:19]
	v_mfma_f32_16x16x32_bf16 v[8:11], v[210:213], v[234:237], v[8:11]
	v_mfma_f32_16x16x32_bf16 v[4:7], v[202:205], v[242:245], v[4:7]
	v_mfma_f32_16x16x32_bf16 v[0:3], v[210:213], v[242:245], v[0:3]
	s_barrier
	s_add_i32 s50, s50, 2
	s_add_u32 s44, s44, 0x100
	s_addc_u32 s45, s45, 0
	s_add_u32 s48, s48, 0x100
	s_addc_u32 s49, s49, 0
	s_cmp_gt_u32 s50, 13
	s_cbranch_scc0 .LBB0_738
	s_and_b64 vcc, exec, s[8:9]
	s_cbranch_vccz .LBB0_741
	s_barrier

.LBB0_758:
	ds_read_b128 v[174:177], v155
	ds_read_b128 v[178:181], v155 offset:1024
	ds_read_b128 v[182:185], v155 offset:2048
	ds_read_b128 v[186:189], v155 offset:3072
	ds_read_b128 v[190:193], v171
	ds_read_b128 v[194:197], v171 offset:1024
	ds_read_b128 v[198:201], v171 offset:2048
	ds_read_b128 v[202:205], v171 offset:3072
	s_add_u32 s44, s42, 0xfffe0080
	s_addc_u32 s45, s43, -1
	s_cmp_eq_u32 s50, 4
	s_cselect_b32 s47, s35, s45
	s_cselect_b32 s46, s36, s44
	s_cselect_b32 s45, s31, s49
	s_cselect_b32 s44, s37, s48
	v_lshl_add_u64 v[130:131], s[42:43], 0, v[144:145]
	s_add_i32 m0, s54, 0xc000
	ds_read_b128 v[206:209], v172
	ds_read_b128 v[210:213], v172 offset:1024
	ds_read_b128 v[214:217], v172 offset:2048
	ds_read_b128 v[218:221], v172 offset:3072
	ds_read_b128 v[222:225], v172 offset:4096
	ds_read_b128 v[226:229], v172 offset:5120
	ds_read_b128 v[230:233], v172 offset:6144
	ds_read_b128 v[234:237], v172 offset:7168
	global_load_lds_dwordx4 v[130:131], off
	v_lshl_add_u64 v[130:131], s[42:43], 0, v[146:147]
	s_add_i32 m0, s54, 0xe000
	s_nop 0
	global_load_lds_dwordx4 v[130:131], off
	s_waitcnt vmcnt(8)
	s_waitcnt lgkmcnt(0)
	s_barrier
	v_mfma_f32_16x16x32_bf16 v[124:127], v[174:177], v[206:209], v[124:127]
	v_mfma_f32_16x16x32_bf16 v[120:123], v[182:185], v[206:209], v[120:123]
	v_mfma_f32_16x16x32_bf16 v[116:119], v[174:177], v[214:217], v[116:119]
	v_mfma_f32_16x16x32_bf16 v[112:115], v[182:185], v[214:217], v[112:115]
	v_mfma_f32_16x16x32_bf16 v[100:103], v[174:177], v[222:225], v[100:103]
	v_mfma_f32_16x16x32_bf16 v[96:99], v[182:185], v[222:225], v[96:99]
	v_mfma_f32_16x16x32_bf16 v[84:87], v[174:177], v[230:233], v[84:87]
	v_mfma_f32_16x16x32_bf16 v[80:83], v[182:185], v[230:233], v[80:83]
	v_mfma_f32_16x16x32_bf16 v[124:127], v[178:181], v[210:213], v[124:127]
	v_mfma_f32_16x16x32_bf16 v[120:123], v[186:189], v[210:213], v[120:123]
	v_mfma_f32_16x16x32_bf16 v[116:119], v[178:181], v[218:221], v[116:119]
	v_mfma_f32_16x16x32_bf16 v[112:115], v[186:189], v[218:221], v[112:115]
	v_mfma_f32_16x16x32_bf16 v[100:103], v[178:181], v[226:229], v[100:103]
	v_mfma_f32_16x16x32_bf16 v[96:99], v[186:189], v[226:229], v[96:99]
	v_mfma_f32_16x16x32_bf16 v[84:87], v[178:181], v[234:237], v[84:87]
	v_mfma_f32_16x16x32_bf16 v[80:83], v[186:189], v[234:237], v[80:83]
	v_mfma_f32_16x16x32_bf16 v[108:111], v[190:193], v[206:209], v[108:111]
	v_mfma_f32_16x16x32_bf16 v[104:107], v[198:201], v[206:209], v[104:107]
	v_mfma_f32_16x16x32_bf16 v[92:95], v[190:193], v[214:217], v[92:95]
	v_mfma_f32_16x16x32_bf16 v[88:91], v[198:201], v[214:217], v[88:91]
	v_mfma_f32_16x16x32_bf16 v[76:79], v[190:193], v[222:225], v[76:79]
	v_mfma_f32_16x16x32_bf16 v[72:75], v[198:201], v[222:225], v[72:75]
	v_mfma_f32_16x16x32_bf16 v[68:71], v[190:193], v[230:233], v[68:71]
	v_mfma_f32_16x16x32_bf16 v[64:67], v[198:201], v[230:233], v[64:67]
	v_mfma_f32_16x16x32_bf16 v[108:111], v[194:197], v[210:213], v[108:111]
	v_mfma_f32_16x16x32_bf16 v[104:107], v[202:205], v[210:213], v[104:107]
	v_mfma_f32_16x16x32_bf16 v[92:95], v[194:197], v[218:221], v[92:95]
	v_mfma_f32_16x16x32_bf16 v[88:91], v[202:205], v[218:221], v[88:91]
	v_mfma_f32_16x16x32_bf16 v[76:79], v[194:197], v[226:229], v[76:79]
	v_mfma_f32_16x16x32_bf16 v[72:75], v[202:205], v[226:229], v[72:75]
	v_mfma_f32_16x16x32_bf16 v[68:71], v[194:197], v[234:237], v[68:71]
	v_mfma_f32_16x16x32_bf16 v[64:67], v[202:205], v[234:237], v[64:67]
	s_barrier
	s_add_i32 s51, s63, s28
	v_lshl_add_u64 v[130:131], s[44:45], 0, v[136:137]
	s_mov_b32 m0, s51
	ds_read_b128 v[206:209], v172 offset:16384
	ds_read_b128 v[210:213], v172 offset:17408
	ds_read_b128 v[214:217], v172 offset:18432
	ds_read_b128 v[218:221], v172 offset:19456
	ds_read_b128 v[222:225], v172 offset:20480
	ds_read_b128 v[226:229], v172 offset:21504
	ds_read_b128 v[230:233], v172 offset:22528
	ds_read_b128 v[234:237], v172 offset:23552
	global_load_lds_dwordx4 v[130:131], off
	s_add_i32 m0, s51, 0x2000
	s_add_u32 s70, s44, 0x20000
	v_lshl_add_u64 v[166:167], s[44:45], 0, v[132:133]
	s_addc_u32 s71, s45, 0
	s_add_i32 s51, s64, s28
	global_load_lds_dwordx4 v[166:167], off
	v_lshl_add_u64 v[238:239], s[70:71], 0, v[136:137]
	s_mov_b32 m0, s51
	v_lshl_add_u64 v[240:241], s[46:47], 0, v[134:135]
	global_load_lds_dwordx4 v[238:239], off
	v_lshl_add_u64 v[238:239], s[70:71], 0, v[132:133]
	s_add_i32 m0, s51, 0x2000
	s_nop 0
	global_load_lds_dwordx4 v[238:239], off
	v_lshl_add_u64 v[238:239], s[46:47], 0, v[138:139]
	s_mov_b32 m0, s54
	s_nop 0
	global_load_lds_dwordx4 v[238:239], off
	s_mov_b32 m0, s55
	s_nop 0
	global_load_lds_dwordx4 v[240:241], off
	s_waitcnt vmcnt(8)
	s_waitcnt lgkmcnt(0)
	s_barrier
	v_mfma_f32_16x16x32_bf16 v[60:63], v[174:177], v[206:209], v[60:63]
	v_mfma_f32_16x16x32_bf16 v[56:59], v[182:185], v[206:209], v[56:59]
	v_mfma_f32_16x16x32_bf16 v[52:55], v[174:177], v[214:217], v[52:55]
	v_mfma_f32_16x16x32_bf16 v[48:51], v[182:185], v[214:217], v[48:51]
	v_mfma_f32_16x16x32_bf16 v[36:39], v[174:177], v[222:225], v[36:39]
	v_mfma_f32_16x16x32_bf16 v[32:35], v[182:185], v[222:225], v[32:35]
	v_mfma_f32_16x16x32_bf16 v[20:23], v[174:177], v[230:233], v[20:23]
	v_mfma_f32_16x16x32_bf16 v[16:19], v[182:185], v[230:233], v[16:19]
	v_mfma_f32_16x16x32_bf16 v[60:63], v[178:181], v[210:213], v[60:63]
	v_mfma_f32_16x16x32_bf16 v[56:59], v[186:189], v[210:213], v[56:59]
	v_mfma_f32_16x16x32_bf16 v[52:55], v[178:181], v[218:221], v[52:55]
	v_mfma_f32_16x16x32_bf16 v[48:51], v[186:189], v[218:221], v[48:51]
	v_mfma_f32_16x16x32_bf16 v[36:39], v[178:181], v[226:229], v[36:39]
	v_mfma_f32_16x16x32_bf16 v[32:35], v[186:189], v[226:229], v[32:35]
	v_mfma_f32_16x16x32_bf16 v[20:23], v[178:181], v[234:237], v[20:23]
	v_mfma_f32_16x16x32_bf16 v[16:19], v[186:189], v[234:237], v[16:19]
	v_mfma_f32_16x16x32_bf16 v[44:47], v[190:193], v[206:209], v[44:47]
	v_mfma_f32_16x16x32_bf16 v[40:43], v[198:201], v[206:209], v[40:43]
	v_mfma_f32_16x16x32_bf16 v[28:31], v[190:193], v[214:217], v[28:31]
	v_mfma_f32_16x16x32_bf16 v[24:27], v[198:201], v[214:217], v[24:27]
	v_mfma_f32_16x16x32_bf16 v[12:15], v[190:193], v[222:225], v[12:15]
	v_mfma_f32_16x16x32_bf16 v[8:11], v[198:201], v[222:225], v[8:11]
	v_mfma_f32_16x16x32_bf16 v[4:7], v[190:193], v[230:233], v[4:7]
	v_mfma_f32_16x16x32_bf16 v[0:3], v[198:201], v[230:233], v[0:3]
	v_mfma_f32_16x16x32_bf16 v[44:47], v[194:197], v[210:213], v[44:47]
	v_mfma_f32_16x16x32_bf16 v[40:43], v[202:205], v[210:213], v[40:43]
	v_mfma_f32_16x16x32_bf16 v[28:31], v[194:197], v[218:221], v[28:31]
	v_mfma_f32_16x16x32_bf16 v[24:27], v[202:205], v[218:221], v[24:27]
	v_mfma_f32_16x16x32_bf16 v[12:15], v[194:197], v[226:229], v[12:15]
	v_mfma_f32_16x16x32_bf16 v[8:11], v[202:205], v[226:229], v[8:11]
	v_mfma_f32_16x16x32_bf16 v[4:7], v[194:197], v[234:237], v[4:7]
	v_mfma_f32_16x16x32_bf16 v[0:3], v[202:205], v[234:237], v[0:3]
	s_barrier
	s_add_i32 s51, 0, 0x18000
	s_add_i32 s70, 0, 0x1c000
	v_add_u32_e32 v186, s51, v153
	v_add_u32_e32 v202, s70, v153
	ds_read_b128 v[174:177], v186
	ds_read_b128 v[178:181], v186 offset:1024
	ds_read_b128 v[182:185], v186 offset:2048
	ds_read_b128 v[186:189], v186 offset:3072
	ds_read_b128 v[190:193], v202
	ds_read_b128 v[194:197], v202 offset:1024
	ds_read_b128 v[198:201], v202 offset:2048
	ds_read_b128 v[202:205], v202 offset:3072
	s_add_u32 s46, s46, 0x20000
	s_addc_u32 s47, s47, 0
	s_mov_b32 m0, s56
	v_lshl_add_u64 v[242:243], s[46:47], 0, v[138:139]
	ds_read_b128 v[206:209], v172 offset:32768
	ds_read_b128 v[210:213], v172 offset:33792
	ds_read_b128 v[214:217], v172 offset:34816
	ds_read_b128 v[218:221], v172 offset:35840
	ds_read_b128 v[222:225], v172 offset:36864
	ds_read_b128 v[226:229], v172 offset:37888
	ds_read_b128 v[230:233], v172 offset:38912
	ds_read_b128 v[234:237], v172 offset:39936
	global_load_lds_dwordx4 v[242:243], off
	v_lshl_add_u64 v[242:243], s[46:47], 0, v[134:135]
	s_mov_b32 m0, s57
	s_nop 0
	global_load_lds_dwordx4 v[242:243], off
	s_waitcnt vmcnt(8)
	s_waitcnt lgkmcnt(0)
	s_barrier
	v_mfma_f32_16x16x32_bf16 v[124:127], v[174:177], v[206:209], v[124:127]
	v_mfma_f32_16x16x32_bf16 v[120:123], v[182:185], v[206:209], v[120:123]
	v_mfma_f32_16x16x32_bf16 v[116:119], v[174:177], v[214:217], v[116:119]
	v_mfma_f32_16x16x32_bf16 v[112:115], v[182:185], v[214:217], v[112:115]
	v_mfma_f32_16x16x32_bf16 v[100:103], v[174:177], v[222:225], v[100:103]
	v_mfma_f32_16x16x32_bf16 v[96:99], v[182:185], v[222:225], v[96:99]
	v_mfma_f32_16x16x32_bf16 v[84:87], v[174:177], v[230:233], v[84:87]
	v_mfma_f32_16x16x32_bf16 v[80:83], v[182:185], v[230:233], v[80:83]
	v_mfma_f32_16x16x32_bf16 v[124:127], v[178:181], v[210:213], v[124:127]
	v_mfma_f32_16x16x32_bf16 v[120:123], v[186:189], v[210:213], v[120:123]
	v_mfma_f32_16x16x32_bf16 v[116:119], v[178:181], v[218:221], v[116:119]
	v_mfma_f32_16x16x32_bf16 v[112:115], v[186:189], v[218:221], v[112:115]
	v_mfma_f32_16x16x32_bf16 v[100:103], v[178:181], v[226:229], v[100:103]
	v_mfma_f32_16x16x32_bf16 v[96:99], v[186:189], v[226:229], v[96:99]
	v_mfma_f32_16x16x32_bf16 v[84:87], v[178:181], v[234:237], v[84:87]
	v_mfma_f32_16x16x32_bf16 v[80:83], v[186:189], v[234:237], v[80:83]
	v_mfma_f32_16x16x32_bf16 v[108:111], v[190:193], v[206:209], v[108:111]
	v_mfma_f32_16x16x32_bf16 v[104:107], v[198:201], v[206:209], v[104:107]
	v_mfma_f32_16x16x32_bf16 v[92:95], v[190:193], v[214:217], v[92:95]
	v_mfma_f32_16x16x32_bf16 v[88:91], v[198:201], v[214:217], v[88:91]
	v_mfma_f32_16x16x32_bf16 v[76:79], v[190:193], v[222:225], v[76:79]
	v_mfma_f32_16x16x32_bf16 v[72:75], v[198:201], v[222:225], v[72:75]
	v_mfma_f32_16x16x32_bf16 v[68:71], v[190:193], v[230:233], v[68:71]
	v_mfma_f32_16x16x32_bf16 v[64:67], v[198:201], v[230:233], v[64:67]
	v_mfma_f32_16x16x32_bf16 v[108:111], v[194:197], v[210:213], v[108:111]
	v_mfma_f32_16x16x32_bf16 v[104:107], v[202:205], v[210:213], v[104:107]
	v_mfma_f32_16x16x32_bf16 v[92:95], v[194:197], v[218:221], v[92:95]
	v_mfma_f32_16x16x32_bf16 v[88:91], v[202:205], v[218:221], v[88:91]
	v_mfma_f32_16x16x32_bf16 v[76:79], v[194:197], v[226:229], v[76:79]
	v_mfma_f32_16x16x32_bf16 v[72:75], v[202:205], v[226:229], v[72:75]
	v_mfma_f32_16x16x32_bf16 v[68:71], v[194:197], v[234:237], v[68:71]
	v_mfma_f32_16x16x32_bf16 v[64:67], v[202:205], v[234:237], v[64:67]
	s_barrier
	s_add_i32 s46, s51, s28
	v_lshl_add_u64 v[130:131], v[130:131], 0, s[8:9]
	s_mov_b32 m0, s46
	ds_read_b128 v[206:209], v172 offset:49152
	ds_read_b128 v[210:213], v172 offset:50176
	ds_read_b128 v[214:217], v172 offset:51200
	ds_read_b128 v[218:221], v172 offset:52224
	ds_read_b128 v[222:225], v172 offset:53248
	ds_read_b128 v[226:229], v172 offset:54272
	ds_read_b128 v[230:233], v172 offset:55296
	ds_read_b128 v[234:237], v172 offset:56320
	global_load_lds_dwordx4 v[130:131], off
	s_add_i32 m0, s46, 0x2000
	s_add_u32 s44, s44, 0x20080
	v_lshl_add_u64 v[130:131], v[166:167], 0, s[8:9]
	s_addc_u32 s45, s45, 0
	s_add_i32 s46, s70, s28
	global_load_lds_dwordx4 v[130:131], off
	v_lshl_add_u64 v[130:131], s[44:45], 0, v[136:137]
	s_mov_b32 m0, s46
	s_nop 0
	global_load_lds_dwordx4 v[130:131], off
	v_lshl_add_u64 v[130:131], s[44:45], 0, v[132:133]
	s_add_i32 m0, s46, 0x2000
	s_nop 0
	global_load_lds_dwordx4 v[130:131], off
	v_lshl_add_u64 v[130:131], v[238:239], 0, s[8:9]
	s_mov_b32 m0, s60
	s_nop 0
	global_load_lds_dwordx4 v[130:131], off
	v_lshl_add_u64 v[130:131], v[240:241], 0, s[8:9]
	s_mov_b32 m0, s61
	s_nop 0
	global_load_lds_dwordx4 v[130:131], off
	s_waitcnt vmcnt(8)
	s_waitcnt lgkmcnt(0)
	s_barrier
	v_mfma_f32_16x16x32_bf16 v[60:63], v[174:177], v[206:209], v[60:63]
	v_mfma_f32_16x16x32_bf16 v[56:59], v[182:185], v[206:209], v[56:59]
	v_mfma_f32_16x16x32_bf16 v[52:55], v[174:177], v[214:217], v[52:55]
	v_mfma_f32_16x16x32_bf16 v[48:51], v[182:185], v[214:217], v[48:51]
	v_mfma_f32_16x16x32_bf16 v[36:39], v[174:177], v[222:225], v[36:39]
	v_mfma_f32_16x16x32_bf16 v[32:35], v[182:185], v[222:225], v[32:35]
	v_mfma_f32_16x16x32_bf16 v[20:23], v[174:177], v[230:233], v[20:23]
	v_mfma_f32_16x16x32_bf16 v[16:19], v[182:185], v[230:233], v[16:19]
	v_mfma_f32_16x16x32_bf16 v[60:63], v[178:181], v[210:213], v[60:63]
	v_mfma_f32_16x16x32_bf16 v[56:59], v[186:189], v[210:213], v[56:59]
	v_mfma_f32_16x16x32_bf16 v[52:55], v[178:181], v[218:221], v[52:55]
	v_mfma_f32_16x16x32_bf16 v[48:51], v[186:189], v[218:221], v[48:51]
	v_mfma_f32_16x16x32_bf16 v[36:39], v[178:181], v[226:229], v[36:39]
	v_mfma_f32_16x16x32_bf16 v[32:35], v[186:189], v[226:229], v[32:35]
	v_mfma_f32_16x16x32_bf16 v[20:23], v[178:181], v[234:237], v[20:23]
	v_mfma_f32_16x16x32_bf16 v[16:19], v[186:189], v[234:237], v[16:19]
	v_mfma_f32_16x16x32_bf16 v[44:47], v[190:193], v[206:209], v[44:47]
	v_mfma_f32_16x16x32_bf16 v[40:43], v[198:201], v[206:209], v[40:43]
	v_mfma_f32_16x16x32_bf16 v[28:31], v[190:193], v[214:217], v[28:31]
	v_mfma_f32_16x16x32_bf16 v[24:27], v[198:201], v[214:217], v[24:27]
	v_mfma_f32_16x16x32_bf16 v[12:15], v[190:193], v[222:225], v[12:15]
	v_mfma_f32_16x16x32_bf16 v[8:11], v[198:201], v[222:225], v[8:11]
	v_mfma_f32_16x16x32_bf16 v[4:7], v[190:193], v[230:233], v[4:7]
	v_mfma_f32_16x16x32_bf16 v[0:3], v[198:201], v[230:233], v[0:3]
	v_mfma_f32_16x16x32_bf16 v[44:47], v[194:197], v[210:213], v[44:47]
	v_mfma_f32_16x16x32_bf16 v[40:43], v[202:205], v[210:213], v[40:43]
	v_mfma_f32_16x16x32_bf16 v[28:31], v[194:197], v[218:221], v[28:31]
	v_mfma_f32_16x16x32_bf16 v[24:27], v[202:205], v[218:221], v[24:27]
	v_mfma_f32_16x16x32_bf16 v[12:15], v[194:197], v[226:229], v[12:15]
	v_mfma_f32_16x16x32_bf16 v[8:11], v[202:205], v[226:229], v[8:11]
	v_mfma_f32_16x16x32_bf16 v[4:7], v[194:197], v[234:237], v[4:7]
	v_mfma_f32_16x16x32_bf16 v[0:3], v[202:205], v[234:237], v[0:3]
	s_barrier
	s_add_i32 s50, s50, 2
	s_add_u32 s42, s42, 0x100
	s_addc_u32 s43, s43, 0
	s_add_u32 s48, s48, 0x100
	s_addc_u32 s49, s49, 0
	s_cmp_gt_u32 s50, 5
	s_cbranch_scc0 .LBB0_758
	s_and_b64 vcc, exec, s[14:15]
	s_cbranch_vccz .LBB0_761
	s_barrier

.LBB0_778:
	ds_read_b128 v[148:151], v144
	ds_read_b128 v[152:155], v144 offset:1024
	ds_read_b128 v[158:161], v144 offset:2048
	ds_read_b128 v[162:165], v144 offset:3072
	ds_read_b128 v[166:169], v145
	ds_read_b128 v[170:173], v145 offset:1024
	ds_read_b128 v[174:177], v145 offset:2048
	ds_read_b128 v[178:181], v145 offset:3072
	s_add_u32 s42, s40, 0xfffe0080
	s_addc_u32 s43, s41, -1
	s_cmp_eq_u32 s61, 4
	s_cselect_b32 s45, s15, s43
	s_cselect_b32 s44, s46, s42
	s_cselect_b32 s43, s9, s51
	s_cselect_b32 s42, s47, s50
	v_lshl_add_u64 v[214:215], s[40:41], 0, v[134:135]
	s_add_i32 m0, s54, 0xc000
	ds_read_b128 v[182:185], v146
	ds_read_b128 v[186:189], v146 offset:1024
	ds_read_b128 v[190:193], v146 offset:2048
	ds_read_b128 v[194:197], v146 offset:3072
	ds_read_b128 v[198:201], v146 offset:4096
	ds_read_b128 v[202:205], v146 offset:5120
	ds_read_b128 v[206:209], v146 offset:6144
	ds_read_b128 v[210:213], v146 offset:7168
	global_load_lds_dwordx4 v[214:215], off
	v_lshl_add_u64 v[214:215], s[40:41], 0, v[136:137]
	s_add_i32 m0, s54, 0xe000
	s_nop 0
	global_load_lds_dwordx4 v[214:215], off
	s_waitcnt vmcnt(8)
	s_waitcnt lgkmcnt(0)
	s_barrier
	v_mfma_f32_16x16x32_bf16 v[124:127], v[148:151], v[182:185], v[124:127]
	v_mfma_f32_16x16x32_bf16 v[104:107], v[158:161], v[182:185], v[104:107]
	v_mfma_f32_16x16x32_bf16 v[120:123], v[148:151], v[190:193], v[120:123]
	v_mfma_f32_16x16x32_bf16 v[96:99], v[158:161], v[190:193], v[96:99]
	v_mfma_f32_16x16x32_bf16 v[116:119], v[148:151], v[198:201], v[116:119]
	v_mfma_f32_16x16x32_bf16 v[88:91], v[158:161], v[198:201], v[88:91]
	v_mfma_f32_16x16x32_bf16 v[112:115], v[148:151], v[206:209], v[112:115]
	v_mfma_f32_16x16x32_bf16 v[80:83], v[158:161], v[206:209], v[80:83]
	v_mfma_f32_16x16x32_bf16 v[124:127], v[152:155], v[186:189], v[124:127]
	v_mfma_f32_16x16x32_bf16 v[104:107], v[162:165], v[186:189], v[104:107]
	v_mfma_f32_16x16x32_bf16 v[120:123], v[152:155], v[194:197], v[120:123]
	v_mfma_f32_16x16x32_bf16 v[96:99], v[162:165], v[194:197], v[96:99]
	v_mfma_f32_16x16x32_bf16 v[116:119], v[152:155], v[202:205], v[116:119]
	v_mfma_f32_16x16x32_bf16 v[88:91], v[162:165], v[202:205], v[88:91]
	v_mfma_f32_16x16x32_bf16 v[112:115], v[152:155], v[210:213], v[112:115]
	v_mfma_f32_16x16x32_bf16 v[80:83], v[162:165], v[210:213], v[80:83]
	v_mfma_f32_16x16x32_bf16 v[64:67], v[166:169], v[182:185], v[64:67]
	v_mfma_f32_16x16x32_bf16 v[40:43], v[174:177], v[182:185], v[40:43]
	v_mfma_f32_16x16x32_bf16 v[56:59], v[166:169], v[190:193], v[56:59]
	v_mfma_f32_16x16x32_bf16 v[32:35], v[174:177], v[190:193], v[32:35]
	v_mfma_f32_16x16x32_bf16 v[52:55], v[166:169], v[198:201], v[52:55]
	v_mfma_f32_16x16x32_bf16 v[24:27], v[174:177], v[198:201], v[24:27]
	v_mfma_f32_16x16x32_bf16 v[48:51], v[166:169], v[206:209], v[48:51]
	v_mfma_f32_16x16x32_bf16 v[16:19], v[174:177], v[206:209], v[16:19]
	v_mfma_f32_16x16x32_bf16 v[64:67], v[170:173], v[186:189], v[64:67]
	v_mfma_f32_16x16x32_bf16 v[40:43], v[178:181], v[186:189], v[40:43]
	v_mfma_f32_16x16x32_bf16 v[56:59], v[170:173], v[194:197], v[56:59]
	v_mfma_f32_16x16x32_bf16 v[32:35], v[178:181], v[194:197], v[32:35]
	v_mfma_f32_16x16x32_bf16 v[52:55], v[170:173], v[202:205], v[52:55]
	v_mfma_f32_16x16x32_bf16 v[24:27], v[178:181], v[202:205], v[24:27]
	v_mfma_f32_16x16x32_bf16 v[48:51], v[170:173], v[210:213], v[48:51]
	v_mfma_f32_16x16x32_bf16 v[16:19], v[178:181], v[210:213], v[16:19]
	s_barrier
	s_add_i32 s62, s48, s28
	v_lshl_add_u64 v[214:215], s[42:43], 0, v[130:131]
	s_mov_b32 m0, s62
	ds_read_b128 v[182:185], v146 offset:16384
	ds_read_b128 v[186:189], v146 offset:17408
	ds_read_b128 v[190:193], v146 offset:18432
	ds_read_b128 v[194:197], v146 offset:19456
	ds_read_b128 v[198:201], v146 offset:20480
	ds_read_b128 v[202:205], v146 offset:21504
	ds_read_b128 v[206:209], v146 offset:22528
	ds_read_b128 v[210:213], v146 offset:23552
	global_load_lds_dwordx4 v[214:215], off
	s_add_i32 m0, s62, 0x2000
	s_add_u32 s62, s42, 0x20000
	v_lshl_add_u64 v[216:217], s[42:43], 0, v[128:129]
	s_addc_u32 s63, s43, 0
	s_add_i32 s64, s49, s28
	global_load_lds_dwordx4 v[216:217], off
	v_lshl_add_u64 v[218:219], s[62:63], 0, v[130:131]
	s_mov_b32 m0, s64
	v_lshl_add_u64 v[220:221], s[44:45], 0, v[128:129]
	global_load_lds_dwordx4 v[218:219], off
	v_lshl_add_u64 v[218:219], s[62:63], 0, v[128:129]
	s_add_i32 m0, s64, 0x2000
	s_nop 0
	global_load_lds_dwordx4 v[218:219], off
	v_lshl_add_u64 v[218:219], s[44:45], 0, v[130:131]
	s_mov_b32 m0, s54
	s_nop 0
	global_load_lds_dwordx4 v[218:219], off
	s_mov_b32 m0, s55
	s_nop 0
	global_load_lds_dwordx4 v[220:221], off
	s_waitcnt vmcnt(8)
	s_waitcnt lgkmcnt(0)
	s_barrier
	v_mfma_f32_16x16x32_bf16 v[108:111], v[148:151], v[182:185], v[108:111]
	v_mfma_f32_16x16x32_bf16 v[76:79], v[158:161], v[182:185], v[76:79]
	v_mfma_f32_16x16x32_bf16 v[100:103], v[148:151], v[190:193], v[100:103]
	v_mfma_f32_16x16x32_bf16 v[72:75], v[158:161], v[190:193], v[72:75]
	v_mfma_f32_16x16x32_bf16 v[92:95], v[148:151], v[198:201], v[92:95]
	v_mfma_f32_16x16x32_bf16 v[68:71], v[158:161], v[198:201], v[68:71]
	v_mfma_f32_16x16x32_bf16 v[84:87], v[148:151], v[206:209], v[84:87]
	v_mfma_f32_16x16x32_bf16 v[60:63], v[158:161], v[206:209], v[60:63]
	v_mfma_f32_16x16x32_bf16 v[108:111], v[152:155], v[186:189], v[108:111]
	v_mfma_f32_16x16x32_bf16 v[76:79], v[162:165], v[186:189], v[76:79]
	v_mfma_f32_16x16x32_bf16 v[100:103], v[152:155], v[194:197], v[100:103]
	v_mfma_f32_16x16x32_bf16 v[72:75], v[162:165], v[194:197], v[72:75]
	v_mfma_f32_16x16x32_bf16 v[92:95], v[152:155], v[202:205], v[92:95]
	v_mfma_f32_16x16x32_bf16 v[68:71], v[162:165], v[202:205], v[68:71]
	v_mfma_f32_16x16x32_bf16 v[84:87], v[152:155], v[210:213], v[84:87]
	v_mfma_f32_16x16x32_bf16 v[60:63], v[162:165], v[210:213], v[60:63]
	v_mfma_f32_16x16x32_bf16 v[44:47], v[166:169], v[182:185], v[44:47]
	v_mfma_f32_16x16x32_bf16 v[12:15], v[174:177], v[182:185], v[12:15]
	v_mfma_f32_16x16x32_bf16 v[36:39], v[166:169], v[190:193], v[36:39]
	v_mfma_f32_16x16x32_bf16 v[8:11], v[174:177], v[190:193], v[8:11]
	v_mfma_f32_16x16x32_bf16 v[28:31], v[166:169], v[198:201], v[28:31]
	v_mfma_f32_16x16x32_bf16 v[4:7], v[174:177], v[198:201], v[4:7]
	v_mfma_f32_16x16x32_bf16 v[20:23], v[166:169], v[206:209], v[20:23]
	v_mfma_f32_16x16x32_bf16 v[0:3], v[174:177], v[206:209], v[0:3]
	v_mfma_f32_16x16x32_bf16 v[44:47], v[170:173], v[186:189], v[44:47]
	v_mfma_f32_16x16x32_bf16 v[12:15], v[178:181], v[186:189], v[12:15]
	v_mfma_f32_16x16x32_bf16 v[36:39], v[170:173], v[194:197], v[36:39]
	v_mfma_f32_16x16x32_bf16 v[8:11], v[178:181], v[194:197], v[8:11]
	v_mfma_f32_16x16x32_bf16 v[28:31], v[170:173], v[202:205], v[28:31]
	v_mfma_f32_16x16x32_bf16 v[4:7], v[178:181], v[202:205], v[4:7]
	v_mfma_f32_16x16x32_bf16 v[20:23], v[170:173], v[210:213], v[20:23]
	v_mfma_f32_16x16x32_bf16 v[0:3], v[178:181], v[210:213], v[0:3]
	s_barrier
	s_add_i32 s62, 0, 0x18000
	v_add_u32_e32 v147, s62, v143
	s_add_i32 s63, 0, 0x1c000
	ds_read_b128 v[148:151], v147
	ds_read_b128 v[152:155], v147 offset:1024
	ds_read_b128 v[158:161], v147 offset:2048
	ds_read_b128 v[162:165], v147 offset:3072
	v_add_u32_e32 v147, s63, v143
	ds_read_b128 v[166:169], v147
	ds_read_b128 v[170:173], v147 offset:1024
	ds_read_b128 v[174:177], v147 offset:2048
	ds_read_b128 v[178:181], v147 offset:3072
	s_add_u32 s44, s44, 0x20000
	s_addc_u32 s45, s45, 0
	s_mov_b32 m0, s56
	v_lshl_add_u64 v[222:223], s[44:45], 0, v[130:131]
	ds_read_b128 v[182:185], v146 offset:32768
	ds_read_b128 v[186:189], v146 offset:33792
	ds_read_b128 v[190:193], v146 offset:34816
	ds_read_b128 v[194:197], v146 offset:35840
	ds_read_b128 v[198:201], v146 offset:36864
	ds_read_b128 v[202:205], v146 offset:37888
	ds_read_b128 v[206:209], v146 offset:38912
	ds_read_b128 v[210:213], v146 offset:39936
	global_load_lds_dwordx4 v[222:223], off
	v_lshl_add_u64 v[222:223], s[44:45], 0, v[128:129]
	s_mov_b32 m0, s57
	s_nop 0
	global_load_lds_dwordx4 v[222:223], off
	s_waitcnt vmcnt(8)
	s_waitcnt lgkmcnt(0)
	s_barrier
	v_mfma_f32_16x16x32_bf16 v[124:127], v[148:151], v[182:185], v[124:127]
	v_mfma_f32_16x16x32_bf16 v[104:107], v[158:161], v[182:185], v[104:107]
	v_mfma_f32_16x16x32_bf16 v[120:123], v[148:151], v[190:193], v[120:123]
	v_mfma_f32_16x16x32_bf16 v[96:99], v[158:161], v[190:193], v[96:99]
	v_mfma_f32_16x16x32_bf16 v[116:119], v[148:151], v[198:201], v[116:119]
	v_mfma_f32_16x16x32_bf16 v[88:91], v[158:161], v[198:201], v[88:91]
	v_mfma_f32_16x16x32_bf16 v[112:115], v[148:151], v[206:209], v[112:115]
	v_mfma_f32_16x16x32_bf16 v[80:83], v[158:161], v[206:209], v[80:83]
	v_mfma_f32_16x16x32_bf16 v[124:127], v[152:155], v[186:189], v[124:127]
	v_mfma_f32_16x16x32_bf16 v[104:107], v[162:165], v[186:189], v[104:107]
	v_mfma_f32_16x16x32_bf16 v[120:123], v[152:155], v[194:197], v[120:123]
	v_mfma_f32_16x16x32_bf16 v[96:99], v[162:165], v[194:197], v[96:99]
	v_mfma_f32_16x16x32_bf16 v[116:119], v[152:155], v[202:205], v[116:119]
	v_mfma_f32_16x16x32_bf16 v[88:91], v[162:165], v[202:205], v[88:91]
	v_mfma_f32_16x16x32_bf16 v[112:115], v[152:155], v[210:213], v[112:115]
	v_mfma_f32_16x16x32_bf16 v[80:83], v[162:165], v[210:213], v[80:83]
	v_mfma_f32_16x16x32_bf16 v[64:67], v[166:169], v[182:185], v[64:67]
	v_mfma_f32_16x16x32_bf16 v[40:43], v[174:177], v[182:185], v[40:43]
	v_mfma_f32_16x16x32_bf16 v[56:59], v[166:169], v[190:193], v[56:59]
	v_mfma_f32_16x16x32_bf16 v[32:35], v[174:177], v[190:193], v[32:35]
	v_mfma_f32_16x16x32_bf16 v[52:55], v[166:169], v[198:201], v[52:55]
	v_mfma_f32_16x16x32_bf16 v[24:27], v[174:177], v[198:201], v[24:27]
	v_mfma_f32_16x16x32_bf16 v[48:51], v[166:169], v[206:209], v[48:51]
	v_mfma_f32_16x16x32_bf16 v[16:19], v[174:177], v[206:209], v[16:19]
	v_mfma_f32_16x16x32_bf16 v[64:67], v[170:173], v[186:189], v[64:67]
	v_mfma_f32_16x16x32_bf16 v[40:43], v[178:181], v[186:189], v[40:43]
	v_mfma_f32_16x16x32_bf16 v[56:59], v[170:173], v[194:197], v[56:59]
	v_mfma_f32_16x16x32_bf16 v[32:35], v[178:181], v[194:197], v[32:35]
	v_mfma_f32_16x16x32_bf16 v[52:55], v[170:173], v[202:205], v[52:55]
	v_mfma_f32_16x16x32_bf16 v[24:27], v[178:181], v[202:205], v[24:27]
	v_mfma_f32_16x16x32_bf16 v[48:51], v[170:173], v[210:213], v[48:51]
	v_mfma_f32_16x16x32_bf16 v[16:19], v[178:181], v[210:213], v[16:19]
	s_barrier
	s_add_i32 s44, s62, s28
	v_lshl_add_u64 v[214:215], v[214:215], 0, s[4:5]
	s_mov_b32 m0, s44
	ds_read_b128 v[182:185], v146 offset:49152
	ds_read_b128 v[186:189], v146 offset:50176
	ds_read_b128 v[190:193], v146 offset:51200
	ds_read_b128 v[194:197], v146 offset:52224
	ds_read_b128 v[198:201], v146 offset:53248
	ds_read_b128 v[202:205], v146 offset:54272
	ds_read_b128 v[206:209], v146 offset:55296
	ds_read_b128 v[210:213], v146 offset:56320
	global_load_lds_dwordx4 v[214:215], off
	s_add_i32 m0, s44, 0x2000
	s_add_u32 s42, s42, 0x20080
	v_lshl_add_u64 v[214:215], v[216:217], 0, s[4:5]
	s_addc_u32 s43, s43, 0
	s_add_i32 s44, s63, s28
	global_load_lds_dwordx4 v[214:215], off
	v_lshl_add_u64 v[214:215], s[42:43], 0, v[130:131]
	s_mov_b32 m0, s44
	s_nop 0
	global_load_lds_dwordx4 v[214:215], off
	v_lshl_add_u64 v[214:215], s[42:43], 0, v[128:129]
	s_add_i32 m0, s44, 0x2000
	s_nop 0
	global_load_lds_dwordx4 v[214:215], off
	v_lshl_add_u64 v[214:215], v[218:219], 0, s[4:5]
	s_mov_b32 m0, s60
	s_nop 0
	global_load_lds_dwordx4 v[214:215], off
	v_lshl_add_u64 v[214:215], v[220:221], 0, s[4:5]
	s_mov_b32 m0, s36
	s_nop 0
	global_load_lds_dwordx4 v[214:215], off
	s_waitcnt vmcnt(8)
	s_waitcnt lgkmcnt(0)
	s_barrier
	v_mfma_f32_16x16x32_bf16 v[108:111], v[148:151], v[182:185], v[108:111]
	v_mfma_f32_16x16x32_bf16 v[76:79], v[158:161], v[182:185], v[76:79]
	v_mfma_f32_16x16x32_bf16 v[100:103], v[148:151], v[190:193], v[100:103]
	v_mfma_f32_16x16x32_bf16 v[72:75], v[158:161], v[190:193], v[72:75]
	v_mfma_f32_16x16x32_bf16 v[92:95], v[148:151], v[198:201], v[92:95]
	v_mfma_f32_16x16x32_bf16 v[68:71], v[158:161], v[198:201], v[68:71]
	v_mfma_f32_16x16x32_bf16 v[84:87], v[148:151], v[206:209], v[84:87]
	v_mfma_f32_16x16x32_bf16 v[60:63], v[158:161], v[206:209], v[60:63]
	v_mfma_f32_16x16x32_bf16 v[108:111], v[152:155], v[186:189], v[108:111]
	v_mfma_f32_16x16x32_bf16 v[76:79], v[162:165], v[186:189], v[76:79]
	v_mfma_f32_16x16x32_bf16 v[100:103], v[152:155], v[194:197], v[100:103]
	v_mfma_f32_16x16x32_bf16 v[72:75], v[162:165], v[194:197], v[72:75]
	v_mfma_f32_16x16x32_bf16 v[92:95], v[152:155], v[202:205], v[92:95]
	v_mfma_f32_16x16x32_bf16 v[68:71], v[162:165], v[202:205], v[68:71]
	v_mfma_f32_16x16x32_bf16 v[84:87], v[152:155], v[210:213], v[84:87]
	v_mfma_f32_16x16x32_bf16 v[60:63], v[162:165], v[210:213], v[60:63]
	v_mfma_f32_16x16x32_bf16 v[44:47], v[166:169], v[182:185], v[44:47]
	v_mfma_f32_16x16x32_bf16 v[12:15], v[174:177], v[182:185], v[12:15]
	v_mfma_f32_16x16x32_bf16 v[36:39], v[166:169], v[190:193], v[36:39]
	v_mfma_f32_16x16x32_bf16 v[8:11], v[174:177], v[190:193], v[8:11]
	v_mfma_f32_16x16x32_bf16 v[28:31], v[166:169], v[198:201], v[28:31]
	v_mfma_f32_16x16x32_bf16 v[4:7], v[174:177], v[198:201], v[4:7]
	v_mfma_f32_16x16x32_bf16 v[20:23], v[166:169], v[206:209], v[20:23]
	v_mfma_f32_16x16x32_bf16 v[0:3], v[174:177], v[206:209], v[0:3]
	v_mfma_f32_16x16x32_bf16 v[44:47], v[170:173], v[186:189], v[44:47]
	v_mfma_f32_16x16x32_bf16 v[12:15], v[178:181], v[186:189], v[12:15]
	v_mfma_f32_16x16x32_bf16 v[36:39], v[170:173], v[194:197], v[36:39]
	v_mfma_f32_16x16x32_bf16 v[8:11], v[178:181], v[194:197], v[8:11]
	v_mfma_f32_16x16x32_bf16 v[28:31], v[170:173], v[202:205], v[28:31]
	v_mfma_f32_16x16x32_bf16 v[4:7], v[178:181], v[202:205], v[4:7]
	v_mfma_f32_16x16x32_bf16 v[20:23], v[170:173], v[210:213], v[20:23]
	v_mfma_f32_16x16x32_bf16 v[0:3], v[178:181], v[210:213], v[0:3]
	s_barrier
	s_add_i32 s61, s61, 2
	s_add_u32 s40, s40, 0x100
	s_addc_u32 s41, s41, 0
	s_add_u32 s50, s50, 0x100
	s_addc_u32 s51, s51, 0
	s_cmp_gt_u32 s61, 5
	s_cbranch_scc0 .LBB0_778
	s_and_b64 vcc, exec, s[6:7]
	s_cbranch_vccz .LBB0_781
	s_barrier

.LBB0_1141:
	ds_read_b128 v[128:131], v177
	ds_read_b128 v[132:135], v177 offset:1024
	ds_read_b128 v[136:139], v177 offset:2048
	ds_read_b128 v[140:143], v177 offset:3072
	ds_read_b128 v[144:147], v178
	ds_read_b128 v[162:165], v178 offset:1024
	ds_read_b128 v[166:169], v178 offset:2048
	ds_read_b128 v[170:173], v178 offset:3072
	s_add_i32 s49, s45, 2
	s_add_u32 s50, s52, 0xfff00080
	s_addc_u32 s51, s53, -1
	s_cmp_eq_u32 s35, s45
	s_cselect_b32 s57, s41, s51
	s_cselect_b32 s56, s40, s50
	s_cselect_b32 s55, s43, s39
	s_cselect_b32 s54, s42, s37
	v_lshl_add_u64 v[214:215], s[52:53], 0, v[156:157]
	s_add_i32 m0, s47, 0xc000
	ds_read_b128 v[180:183], v179
	ds_read_b128 v[184:187], v179 offset:1024
	ds_read_b128 v[188:191], v179 offset:2048
	ds_read_b128 v[192:195], v179 offset:3072
	ds_read_b128 v[196:199], v179 offset:4096
	ds_read_b128 v[202:205], v179 offset:5120
	ds_read_b128 v[206:209], v179 offset:6144
	ds_read_b128 v[210:213], v179 offset:7168
	global_load_lds_dwordx4 v[214:215], off
	v_lshl_add_u64 v[214:215], s[52:53], 0, v[158:159]
	s_add_i32 m0, s47, 0xe000
	s_nop 0
	global_load_lds_dwordx4 v[214:215], off
	s_waitcnt vmcnt(8)
	s_waitcnt lgkmcnt(0)
	s_barrier
	v_mfma_f32_16x16x32_bf16 v[124:127], v[128:131], v[180:183], v[124:127]
	v_mfma_f32_16x16x32_bf16 v[120:123], v[136:139], v[180:183], v[120:123]
	v_mfma_f32_16x16x32_bf16 v[108:111], v[128:131], v[188:191], v[108:111]
	v_mfma_f32_16x16x32_bf16 v[104:107], v[136:139], v[188:191], v[104:107]
	v_mfma_f32_16x16x32_bf16 v[92:95], v[128:131], v[196:199], v[92:95]
	v_mfma_f32_16x16x32_bf16 v[88:91], v[136:139], v[196:199], v[88:91]
	v_mfma_f32_16x16x32_bf16 v[76:79], v[128:131], v[206:209], v[76:79]
	v_mfma_f32_16x16x32_bf16 v[72:75], v[136:139], v[206:209], v[72:75]
	v_mfma_f32_16x16x32_bf16 v[124:127], v[132:135], v[184:187], v[124:127]
	v_mfma_f32_16x16x32_bf16 v[120:123], v[140:143], v[184:187], v[120:123]
	v_mfma_f32_16x16x32_bf16 v[108:111], v[132:135], v[192:195], v[108:111]
	v_mfma_f32_16x16x32_bf16 v[104:107], v[140:143], v[192:195], v[104:107]
	v_mfma_f32_16x16x32_bf16 v[92:95], v[132:135], v[202:205], v[92:95]
	v_mfma_f32_16x16x32_bf16 v[88:91], v[140:143], v[202:205], v[88:91]
	v_mfma_f32_16x16x32_bf16 v[76:79], v[132:135], v[210:213], v[76:79]
	v_mfma_f32_16x16x32_bf16 v[72:75], v[140:143], v[210:213], v[72:75]
	v_mfma_f32_16x16x32_bf16 v[116:119], v[144:147], v[180:183], v[116:119]
	v_mfma_f32_16x16x32_bf16 v[112:115], v[166:169], v[180:183], v[112:115]
	v_mfma_f32_16x16x32_bf16 v[100:103], v[144:147], v[188:191], v[100:103]
	v_mfma_f32_16x16x32_bf16 v[96:99], v[166:169], v[188:191], v[96:99]
	v_mfma_f32_16x16x32_bf16 v[84:87], v[144:147], v[196:199], v[84:87]
	v_mfma_f32_16x16x32_bf16 v[80:83], v[166:169], v[196:199], v[80:83]
	v_mfma_f32_16x16x32_bf16 v[68:71], v[144:147], v[206:209], v[68:71]
	v_mfma_f32_16x16x32_bf16 v[64:67], v[166:169], v[206:209], v[64:67]
	v_mfma_f32_16x16x32_bf16 v[116:119], v[162:165], v[184:187], v[116:119]
	v_mfma_f32_16x16x32_bf16 v[112:115], v[170:173], v[184:187], v[112:115]
	v_mfma_f32_16x16x32_bf16 v[100:103], v[162:165], v[192:195], v[100:103]
	v_mfma_f32_16x16x32_bf16 v[96:99], v[170:173], v[192:195], v[96:99]
	v_mfma_f32_16x16x32_bf16 v[84:87], v[162:165], v[202:205], v[84:87]
	v_mfma_f32_16x16x32_bf16 v[80:83], v[170:173], v[202:205], v[80:83]
	v_mfma_f32_16x16x32_bf16 v[68:71], v[162:165], v[210:213], v[68:71]
	v_mfma_f32_16x16x32_bf16 v[64:67], v[170:173], v[210:213], v[64:67]
	s_barrier
	s_add_i32 s45, s67, s33
	v_lshl_add_u64 v[214:215], s[54:55], 0, v[150:151]
	s_mov_b32 m0, s45
	ds_read_b128 v[180:183], v179 offset:16384
	ds_read_b128 v[184:187], v179 offset:17408
	ds_read_b128 v[188:191], v179 offset:18432
	ds_read_b128 v[192:195], v179 offset:19456
	ds_read_b128 v[196:199], v179 offset:20480
	ds_read_b128 v[202:205], v179 offset:21504
	ds_read_b128 v[206:209], v179 offset:22528
	ds_read_b128 v[210:213], v179 offset:23552
	global_load_lds_dwordx4 v[214:215], off
	s_add_i32 m0, s45, 0x2000
	s_add_u32 s50, s54, 0x100000
	v_lshl_add_u64 v[216:217], s[54:55], 0, v[154:155]
	s_addc_u32 s51, s55, 0
	s_add_i32 s45, s68, s33
	global_load_lds_dwordx4 v[216:217], off
	v_lshl_add_u64 v[218:219], s[50:51], 0, v[150:151]
	s_mov_b32 m0, s45
	v_lshl_add_u64 v[220:221], s[56:57], 0, v[152:153]
	global_load_lds_dwordx4 v[218:219], off
	v_lshl_add_u64 v[218:219], s[50:51], 0, v[154:155]
	s_add_i32 m0, s45, 0x2000
	s_nop 0
	global_load_lds_dwordx4 v[218:219], off
	v_lshl_add_u64 v[218:219], s[56:57], 0, v[148:149]
	s_mov_b32 m0, s47
	s_nop 0
	global_load_lds_dwordx4 v[218:219], off
	s_mov_b32 m0, s60
	s_nop 0
	global_load_lds_dwordx4 v[220:221], off
	s_waitcnt vmcnt(8)
	s_waitcnt lgkmcnt(0)
	s_barrier
	v_mfma_f32_16x16x32_bf16 v[60:63], v[128:131], v[180:183], v[60:63]
	v_mfma_f32_16x16x32_bf16 v[56:59], v[136:139], v[180:183], v[56:59]
	v_mfma_f32_16x16x32_bf16 v[44:47], v[128:131], v[188:191], v[44:47]
	v_mfma_f32_16x16x32_bf16 v[40:43], v[136:139], v[188:191], v[40:43]
	v_mfma_f32_16x16x32_bf16 v[28:31], v[128:131], v[196:199], v[28:31]
	v_mfma_f32_16x16x32_bf16 v[24:27], v[136:139], v[196:199], v[24:27]
	v_mfma_f32_16x16x32_bf16 v[12:15], v[128:131], v[206:209], v[12:15]
	v_mfma_f32_16x16x32_bf16 v[8:11], v[136:139], v[206:209], v[8:11]
	v_mfma_f32_16x16x32_bf16 v[60:63], v[132:135], v[184:187], v[60:63]
	v_mfma_f32_16x16x32_bf16 v[56:59], v[140:143], v[184:187], v[56:59]
	v_mfma_f32_16x16x32_bf16 v[44:47], v[132:135], v[192:195], v[44:47]
	v_mfma_f32_16x16x32_bf16 v[40:43], v[140:143], v[192:195], v[40:43]
	v_mfma_f32_16x16x32_bf16 v[28:31], v[132:135], v[202:205], v[28:31]
	v_mfma_f32_16x16x32_bf16 v[24:27], v[140:143], v[202:205], v[24:27]
	v_mfma_f32_16x16x32_bf16 v[12:15], v[132:135], v[210:213], v[12:15]
	v_mfma_f32_16x16x32_bf16 v[8:11], v[140:143], v[210:213], v[8:11]
	v_mfma_f32_16x16x32_bf16 v[52:55], v[144:147], v[180:183], v[52:55]
	v_mfma_f32_16x16x32_bf16 v[48:51], v[166:169], v[180:183], v[48:51]
	v_mfma_f32_16x16x32_bf16 v[36:39], v[144:147], v[188:191], v[36:39]
	v_mfma_f32_16x16x32_bf16 v[32:35], v[166:169], v[188:191], v[32:35]
	v_mfma_f32_16x16x32_bf16 v[20:23], v[144:147], v[196:199], v[20:23]
	v_mfma_f32_16x16x32_bf16 v[16:19], v[166:169], v[196:199], v[16:19]
	v_mfma_f32_16x16x32_bf16 v[4:7], v[144:147], v[206:209], v[4:7]
	v_mfma_f32_16x16x32_bf16 v[0:3], v[166:169], v[206:209], v[0:3]
	v_mfma_f32_16x16x32_bf16 v[52:55], v[162:165], v[184:187], v[52:55]
	v_mfma_f32_16x16x32_bf16 v[48:51], v[170:173], v[184:187], v[48:51]
	v_mfma_f32_16x16x32_bf16 v[36:39], v[162:165], v[192:195], v[36:39]
	v_mfma_f32_16x16x32_bf16 v[32:35], v[170:173], v[192:195], v[32:35]
	v_mfma_f32_16x16x32_bf16 v[20:23], v[162:165], v[202:205], v[20:23]
	v_mfma_f32_16x16x32_bf16 v[16:19], v[170:173], v[202:205], v[16:19]
	v_mfma_f32_16x16x32_bf16 v[4:7], v[162:165], v[210:213], v[4:7]
	v_mfma_f32_16x16x32_bf16 v[0:3], v[170:173], v[210:213], v[0:3]
	s_barrier
	s_add_i32 s45, 0, 0x18000
	s_add_i32 s72, 0, 0x1c000
	v_add_u32_e32 v140, s45, v175
	v_add_u32_e32 v170, s72, v175
	ds_read_b128 v[128:131], v140
	ds_read_b128 v[132:135], v140 offset:1024
	ds_read_b128 v[136:139], v140 offset:2048
	ds_read_b128 v[140:143], v140 offset:3072
	ds_read_b128 v[144:147], v170
	ds_read_b128 v[162:165], v170 offset:1024
	ds_read_b128 v[166:169], v170 offset:2048
	ds_read_b128 v[170:173], v170 offset:3072
	s_add_u32 s50, s56, 0x100000
	s_addc_u32 s51, s57, 0
	s_mov_b32 m0, s61
	v_lshl_add_u64 v[222:223], s[50:51], 0, v[148:149]
	ds_read_b128 v[180:183], v179 offset:32768
	ds_read_b128 v[184:187], v179 offset:33792
	ds_read_b128 v[188:191], v179 offset:34816
	ds_read_b128 v[192:195], v179 offset:35840
	ds_read_b128 v[196:199], v179 offset:36864
	ds_read_b128 v[202:205], v179 offset:37888
	ds_read_b128 v[206:209], v179 offset:38912
	ds_read_b128 v[210:213], v179 offset:39936
	global_load_lds_dwordx4 v[222:223], off
	v_lshl_add_u64 v[222:223], s[50:51], 0, v[152:153]
	s_mov_b32 m0, s62
	s_nop 0
	global_load_lds_dwordx4 v[222:223], off
	s_waitcnt vmcnt(8)
	s_waitcnt lgkmcnt(0)
	s_barrier
	v_mfma_f32_16x16x32_bf16 v[124:127], v[128:131], v[180:183], v[124:127]
	v_mfma_f32_16x16x32_bf16 v[120:123], v[136:139], v[180:183], v[120:123]
	v_mfma_f32_16x16x32_bf16 v[108:111], v[128:131], v[188:191], v[108:111]
	v_mfma_f32_16x16x32_bf16 v[104:107], v[136:139], v[188:191], v[104:107]
	v_mfma_f32_16x16x32_bf16 v[92:95], v[128:131], v[196:199], v[92:95]
	v_mfma_f32_16x16x32_bf16 v[88:91], v[136:139], v[196:199], v[88:91]
	v_mfma_f32_16x16x32_bf16 v[76:79], v[128:131], v[206:209], v[76:79]
	v_mfma_f32_16x16x32_bf16 v[72:75], v[136:139], v[206:209], v[72:75]
	v_mfma_f32_16x16x32_bf16 v[124:127], v[132:135], v[184:187], v[124:127]
	v_mfma_f32_16x16x32_bf16 v[120:123], v[140:143], v[184:187], v[120:123]
	v_mfma_f32_16x16x32_bf16 v[108:111], v[132:135], v[192:195], v[108:111]
	v_mfma_f32_16x16x32_bf16 v[104:107], v[140:143], v[192:195], v[104:107]
	v_mfma_f32_16x16x32_bf16 v[92:95], v[132:135], v[202:205], v[92:95]
	v_mfma_f32_16x16x32_bf16 v[88:91], v[140:143], v[202:205], v[88:91]
	v_mfma_f32_16x16x32_bf16 v[76:79], v[132:135], v[210:213], v[76:79]
	v_mfma_f32_16x16x32_bf16 v[72:75], v[140:143], v[210:213], v[72:75]
	v_mfma_f32_16x16x32_bf16 v[116:119], v[144:147], v[180:183], v[116:119]
	v_mfma_f32_16x16x32_bf16 v[112:115], v[166:169], v[180:183], v[112:115]
	v_mfma_f32_16x16x32_bf16 v[100:103], v[144:147], v[188:191], v[100:103]
	v_mfma_f32_16x16x32_bf16 v[96:99], v[166:169], v[188:191], v[96:99]
	v_mfma_f32_16x16x32_bf16 v[84:87], v[144:147], v[196:199], v[84:87]
	v_mfma_f32_16x16x32_bf16 v[80:83], v[166:169], v[196:199], v[80:83]
	v_mfma_f32_16x16x32_bf16 v[68:71], v[144:147], v[206:209], v[68:71]
	v_mfma_f32_16x16x32_bf16 v[64:67], v[166:169], v[206:209], v[64:67]
	v_mfma_f32_16x16x32_bf16 v[116:119], v[162:165], v[184:187], v[116:119]
	v_mfma_f32_16x16x32_bf16 v[112:115], v[170:173], v[184:187], v[112:115]
	v_mfma_f32_16x16x32_bf16 v[100:103], v[162:165], v[192:195], v[100:103]
	v_mfma_f32_16x16x32_bf16 v[96:99], v[170:173], v[192:195], v[96:99]
	v_mfma_f32_16x16x32_bf16 v[84:87], v[162:165], v[202:205], v[84:87]
	v_mfma_f32_16x16x32_bf16 v[80:83], v[170:173], v[202:205], v[80:83]
	v_mfma_f32_16x16x32_bf16 v[68:71], v[162:165], v[210:213], v[68:71]
	v_mfma_f32_16x16x32_bf16 v[64:67], v[170:173], v[210:213], v[64:67]
	s_barrier
	s_add_i32 s45, s45, s33
	v_lshl_add_u64 v[214:215], v[214:215], 0, s[10:11]
	s_mov_b32 m0, s45
	ds_read_b128 v[180:183], v179 offset:49152
	ds_read_b128 v[184:187], v179 offset:50176
	ds_read_b128 v[188:191], v179 offset:51200
	ds_read_b128 v[192:195], v179 offset:52224
	ds_read_b128 v[196:199], v179 offset:53248
	ds_read_b128 v[202:205], v179 offset:54272
	ds_read_b128 v[206:209], v179 offset:55296
	ds_read_b128 v[210:213], v179 offset:56320
	global_load_lds_dwordx4 v[214:215], off
	s_add_i32 m0, s45, 0x2000
	s_add_u32 s50, s54, 0x100080
	v_lshl_add_u64 v[214:215], v[216:217], 0, s[10:11]
	s_addc_u32 s51, s55, 0
	s_add_i32 s45, s72, s33
	global_load_lds_dwordx4 v[214:215], off
	v_lshl_add_u64 v[214:215], s[50:51], 0, v[150:151]
	s_mov_b32 m0, s45
	s_nop 0
	global_load_lds_dwordx4 v[214:215], off
	v_lshl_add_u64 v[214:215], s[50:51], 0, v[154:155]
	s_add_i32 m0, s45, 0x2000
	s_nop 0
	global_load_lds_dwordx4 v[214:215], off
	v_lshl_add_u64 v[214:215], v[218:219], 0, s[10:11]
	s_mov_b32 m0, s63
	s_nop 0
	global_load_lds_dwordx4 v[214:215], off
	v_lshl_add_u64 v[214:215], v[220:221], 0, s[10:11]
	s_mov_b32 m0, s64
	s_nop 0
	global_load_lds_dwordx4 v[214:215], off
	s_waitcnt vmcnt(8)
	s_waitcnt lgkmcnt(0)
	s_barrier
	v_mfma_f32_16x16x32_bf16 v[60:63], v[128:131], v[180:183], v[60:63]
	v_mfma_f32_16x16x32_bf16 v[56:59], v[136:139], v[180:183], v[56:59]
	v_mfma_f32_16x16x32_bf16 v[44:47], v[128:131], v[188:191], v[44:47]
	v_mfma_f32_16x16x32_bf16 v[40:43], v[136:139], v[188:191], v[40:43]
	v_mfma_f32_16x16x32_bf16 v[28:31], v[128:131], v[196:199], v[28:31]
	v_mfma_f32_16x16x32_bf16 v[24:27], v[136:139], v[196:199], v[24:27]
	v_mfma_f32_16x16x32_bf16 v[12:15], v[128:131], v[206:209], v[12:15]
	v_mfma_f32_16x16x32_bf16 v[8:11], v[136:139], v[206:209], v[8:11]
	v_mfma_f32_16x16x32_bf16 v[60:63], v[132:135], v[184:187], v[60:63]
	v_mfma_f32_16x16x32_bf16 v[56:59], v[140:143], v[184:187], v[56:59]
	v_mfma_f32_16x16x32_bf16 v[44:47], v[132:135], v[192:195], v[44:47]
	v_mfma_f32_16x16x32_bf16 v[40:43], v[140:143], v[192:195], v[40:43]
	v_mfma_f32_16x16x32_bf16 v[28:31], v[132:135], v[202:205], v[28:31]
	v_mfma_f32_16x16x32_bf16 v[24:27], v[140:143], v[202:205], v[24:27]
	v_mfma_f32_16x16x32_bf16 v[12:15], v[132:135], v[210:213], v[12:15]
	v_mfma_f32_16x16x32_bf16 v[8:11], v[140:143], v[210:213], v[8:11]
	v_mfma_f32_16x16x32_bf16 v[52:55], v[144:147], v[180:183], v[52:55]
	v_mfma_f32_16x16x32_bf16 v[48:51], v[166:169], v[180:183], v[48:51]
	v_mfma_f32_16x16x32_bf16 v[36:39], v[144:147], v[188:191], v[36:39]
	v_mfma_f32_16x16x32_bf16 v[32:35], v[166:169], v[188:191], v[32:35]
	v_mfma_f32_16x16x32_bf16 v[20:23], v[144:147], v[196:199], v[20:23]
	v_mfma_f32_16x16x32_bf16 v[16:19], v[166:169], v[196:199], v[16:19]
	v_mfma_f32_16x16x32_bf16 v[4:7], v[144:147], v[206:209], v[4:7]
	v_mfma_f32_16x16x32_bf16 v[0:3], v[166:169], v[206:209], v[0:3]
	v_mfma_f32_16x16x32_bf16 v[52:55], v[162:165], v[184:187], v[52:55]
	v_mfma_f32_16x16x32_bf16 v[48:51], v[170:173], v[184:187], v[48:51]
	v_mfma_f32_16x16x32_bf16 v[36:39], v[162:165], v[192:195], v[36:39]
	v_mfma_f32_16x16x32_bf16 v[32:35], v[170:173], v[192:195], v[32:35]
	v_mfma_f32_16x16x32_bf16 v[20:23], v[162:165], v[202:205], v[20:23]
	v_mfma_f32_16x16x32_bf16 v[16:19], v[170:173], v[202:205], v[16:19]
	v_mfma_f32_16x16x32_bf16 v[4:7], v[162:165], v[210:213], v[4:7]
	v_mfma_f32_16x16x32_bf16 v[0:3], v[170:173], v[210:213], v[0:3]
	s_barrier
	s_add_u32 s52, s52, 0x100
	s_addc_u32 s53, s53, 0
	s_add_u32 s37, s37, 0x100
	s_addc_u32 s39, s39, 0
	s_cmp_ge_i32 s49, s48
	s_mov_b32 s45, s49
	s_cbranch_scc0 .LBB0_1141
	s_and_b64 vcc, exec, s[14:15]
	s_cbranch_vccz .LBB0_1144

.LBB0_1299:
	ds_read_b128 v[144:147], v153 offset:0
	ds_read_b128 v[156:159], v153 offset:1024
	ds_read_b128 v[160:163], v153 offset:2048
	ds_read_b128 v[164:167], v153 offset:3072
	ds_read_b128 v[168:171], v154 offset:0
	ds_read_b128 v[172:175], v154 offset:1024
	ds_read_b128 v[176:179], v154 offset:2048
	ds_read_b128 v[180:183], v154 offset:3072
	s_add_u32 s36, s34, 0xfff00080
	s_addc_u32 s37, s35, -1
	s_cmp_eq_u32 s57, 60
	s_cselect_b32 s39, s13, s37
	s_cselect_b32 s38, s53, s36
	s_cselect_b32 s37, s11, s56
	s_cselect_b32 s36, s54, s55
	ds_read_b128 v[184:187], v155 offset:0
	ds_read_b128 v[188:191], v155 offset:1024
	ds_read_b128 v[192:195], v155 offset:2048
	ds_read_b128 v[196:199], v155 offset:3072
	ds_read_b128 v[202:205], v155 offset:4096
	ds_read_b128 v[206:209], v155 offset:5120
	ds_read_b128 v[210:213], v155 offset:6144
	ds_read_b128 v[214:217], v155 offset:7168
	s_add_i32 m0, s31, 0xc000
	s_nop 0
	global_load_lds_dwordx4 v136, s[34:35]
	s_add_i32 m0, s31, 0xe000
	s_nop 0
	global_load_lds_dwordx4 v138, s[34:35]
	s_waitcnt vmcnt(8)
	s_waitcnt lgkmcnt(0)
	s_barrier
	v_mfma_f32_16x16x32_bf16 v[124:127], v[144:147], v[184:187], v[124:127]
	v_mfma_f32_16x16x32_bf16 v[120:123], v[160:163], v[184:187], v[120:123]
	v_mfma_f32_16x16x32_bf16 v[108:111], v[144:147], v[192:195], v[108:111]
	v_mfma_f32_16x16x32_bf16 v[104:107], v[160:163], v[192:195], v[104:107]
	v_mfma_f32_16x16x32_bf16 v[92:95], v[144:147], v[202:205], v[92:95]
	v_mfma_f32_16x16x32_bf16 v[88:91], v[160:163], v[202:205], v[88:91]
	v_mfma_f32_16x16x32_bf16 v[76:79], v[144:147], v[210:213], v[76:79]
	v_mfma_f32_16x16x32_bf16 v[72:75], v[160:163], v[210:213], v[72:75]
	v_mfma_f32_16x16x32_bf16 v[124:127], v[156:159], v[188:191], v[124:127]
	v_mfma_f32_16x16x32_bf16 v[120:123], v[164:167], v[188:191], v[120:123]
	v_mfma_f32_16x16x32_bf16 v[108:111], v[156:159], v[196:199], v[108:111]
	v_mfma_f32_16x16x32_bf16 v[104:107], v[164:167], v[196:199], v[104:107]
	v_mfma_f32_16x16x32_bf16 v[92:95], v[156:159], v[206:209], v[92:95]
	v_mfma_f32_16x16x32_bf16 v[88:91], v[164:167], v[206:209], v[88:91]
	v_mfma_f32_16x16x32_bf16 v[76:79], v[156:159], v[214:217], v[76:79]
	v_mfma_f32_16x16x32_bf16 v[72:75], v[164:167], v[214:217], v[72:75]
	v_mfma_f32_16x16x32_bf16 v[116:119], v[168:171], v[184:187], v[116:119]
	v_mfma_f32_16x16x32_bf16 v[112:115], v[176:179], v[184:187], v[112:115]
	v_mfma_f32_16x16x32_bf16 v[100:103], v[168:171], v[192:195], v[100:103]
	v_mfma_f32_16x16x32_bf16 v[96:99], v[176:179], v[192:195], v[96:99]
	v_mfma_f32_16x16x32_bf16 v[84:87], v[168:171], v[202:205], v[84:87]
	v_mfma_f32_16x16x32_bf16 v[80:83], v[176:179], v[202:205], v[80:83]
	v_mfma_f32_16x16x32_bf16 v[68:71], v[168:171], v[210:213], v[68:71]
	v_mfma_f32_16x16x32_bf16 v[64:67], v[176:179], v[210:213], v[64:67]
	v_mfma_f32_16x16x32_bf16 v[116:119], v[172:175], v[188:191], v[116:119]
	v_mfma_f32_16x16x32_bf16 v[112:115], v[180:183], v[188:191], v[112:115]
	v_mfma_f32_16x16x32_bf16 v[100:103], v[172:175], v[196:199], v[100:103]
	v_mfma_f32_16x16x32_bf16 v[96:99], v[180:183], v[196:199], v[96:99]
	v_mfma_f32_16x16x32_bf16 v[84:87], v[172:175], v[206:209], v[84:87]
	v_mfma_f32_16x16x32_bf16 v[80:83], v[180:183], v[206:209], v[80:83]
	v_mfma_f32_16x16x32_bf16 v[68:71], v[172:175], v[214:217], v[68:71]
	v_mfma_f32_16x16x32_bf16 v[64:67], v[180:183], v[214:217], v[64:67]
	s_barrier
	s_add_u32 s58, s36, 0x100000
	s_addc_u32 s59, s37, 0
	ds_read_b128 v[184:187], v155 offset:16384
	ds_read_b128 v[188:191], v155 offset:17408
	ds_read_b128 v[192:195], v155 offset:18432
	ds_read_b128 v[196:199], v155 offset:19456
	ds_read_b128 v[202:205], v155 offset:20480
	ds_read_b128 v[206:209], v155 offset:21504
	ds_read_b128 v[210:213], v155 offset:22528
	ds_read_b128 v[214:217], v155 offset:23552
	s_add_i32 m0, s31, 0x10000
	s_nop 0
	global_load_lds_dwordx4 v130, s[36:37]
	s_add_i32 m0, s31, 0x12000
	s_nop 0
	global_load_lds_dwordx4 v134, s[36:37]
	s_add_i32 m0, s31, 0x14000
	s_nop 0
	global_load_lds_dwordx4 v130, s[58:59]
	s_add_i32 m0, s31, 0x16000
	s_nop 0
	global_load_lds_dwordx4 v134, s[58:59]
	s_add_i32 m0, s31, 0x0
	s_nop 0
	global_load_lds_dwordx4 v128, s[38:39]
	s_add_i32 m0, s31, 0x2000
	s_nop 0
	global_load_lds_dwordx4 v132, s[38:39]
	s_waitcnt vmcnt(8)
	s_waitcnt lgkmcnt(0)
	s_barrier
	v_mfma_f32_16x16x32_bf16 v[60:63], v[144:147], v[184:187], v[60:63]
	v_mfma_f32_16x16x32_bf16 v[56:59], v[160:163], v[184:187], v[56:59]
	v_mfma_f32_16x16x32_bf16 v[44:47], v[144:147], v[192:195], v[44:47]
	v_mfma_f32_16x16x32_bf16 v[40:43], v[160:163], v[192:195], v[40:43]
	v_mfma_f32_16x16x32_bf16 v[28:31], v[144:147], v[202:205], v[28:31]
	v_mfma_f32_16x16x32_bf16 v[24:27], v[160:163], v[202:205], v[24:27]
	v_mfma_f32_16x16x32_bf16 v[12:15], v[144:147], v[210:213], v[12:15]
	v_mfma_f32_16x16x32_bf16 v[8:11], v[160:163], v[210:213], v[8:11]
	v_mfma_f32_16x16x32_bf16 v[60:63], v[156:159], v[188:191], v[60:63]
	v_mfma_f32_16x16x32_bf16 v[56:59], v[164:167], v[188:191], v[56:59]
	v_mfma_f32_16x16x32_bf16 v[44:47], v[156:159], v[196:199], v[44:47]
	v_mfma_f32_16x16x32_bf16 v[40:43], v[164:167], v[196:199], v[40:43]
	v_mfma_f32_16x16x32_bf16 v[28:31], v[156:159], v[206:209], v[28:31]
	v_mfma_f32_16x16x32_bf16 v[24:27], v[164:167], v[206:209], v[24:27]
	v_mfma_f32_16x16x32_bf16 v[12:15], v[156:159], v[214:217], v[12:15]
	v_mfma_f32_16x16x32_bf16 v[8:11], v[164:167], v[214:217], v[8:11]
	v_mfma_f32_16x16x32_bf16 v[52:55], v[168:171], v[184:187], v[52:55]
	v_mfma_f32_16x16x32_bf16 v[48:51], v[176:179], v[184:187], v[48:51]
	v_mfma_f32_16x16x32_bf16 v[36:39], v[168:171], v[192:195], v[36:39]
	v_mfma_f32_16x16x32_bf16 v[32:35], v[176:179], v[192:195], v[32:35]
	v_mfma_f32_16x16x32_bf16 v[20:23], v[168:171], v[202:205], v[20:23]
	v_mfma_f32_16x16x32_bf16 v[16:19], v[176:179], v[202:205], v[16:19]
	v_mfma_f32_16x16x32_bf16 v[4:7], v[168:171], v[210:213], v[4:7]
	v_mfma_f32_16x16x32_bf16 v[0:3], v[176:179], v[210:213], v[0:3]
	v_mfma_f32_16x16x32_bf16 v[52:55], v[172:175], v[188:191], v[52:55]
	v_mfma_f32_16x16x32_bf16 v[48:51], v[180:183], v[188:191], v[48:51]
	v_mfma_f32_16x16x32_bf16 v[36:39], v[172:175], v[196:199], v[36:39]
	v_mfma_f32_16x16x32_bf16 v[32:35], v[180:183], v[196:199], v[32:35]
	v_mfma_f32_16x16x32_bf16 v[20:23], v[172:175], v[206:209], v[20:23]
	v_mfma_f32_16x16x32_bf16 v[16:19], v[180:183], v[206:209], v[16:19]
	v_mfma_f32_16x16x32_bf16 v[4:7], v[172:175], v[214:217], v[4:7]
	v_mfma_f32_16x16x32_bf16 v[0:3], v[180:183], v[214:217], v[0:3]
	s_barrier
	s_add_u32 s98, s38, 0x100000
	s_addc_u32 s99, s39, 0
	ds_read_b128 v[144:147], v153 offset:32768
	ds_read_b128 v[156:159], v153 offset:33792
	ds_read_b128 v[160:163], v153 offset:34816
	ds_read_b128 v[164:167], v153 offset:35840
	ds_read_b128 v[168:171], v154 offset:32768
	ds_read_b128 v[172:175], v154 offset:33792
	ds_read_b128 v[176:179], v154 offset:34816
	ds_read_b128 v[180:183], v154 offset:35840
	ds_read_b128 v[184:187], v155 offset:32768
	ds_read_b128 v[188:191], v155 offset:33792
	ds_read_b128 v[192:195], v155 offset:34816
	ds_read_b128 v[196:199], v155 offset:35840
	ds_read_b128 v[202:205], v155 offset:36864
	ds_read_b128 v[206:209], v155 offset:37888
	ds_read_b128 v[210:213], v155 offset:38912
	ds_read_b128 v[214:217], v155 offset:39936
	s_add_i32 m0, s31, 0x4000
	s_nop 0
	global_load_lds_dwordx4 v128, s[98:99]
	s_add_i32 m0, s31, 0x6000
	s_nop 0
	global_load_lds_dwordx4 v132, s[98:99]
	s_waitcnt vmcnt(8)
	s_waitcnt lgkmcnt(0)
	s_barrier
	v_mfma_f32_16x16x32_bf16 v[124:127], v[144:147], v[184:187], v[124:127]
	v_mfma_f32_16x16x32_bf16 v[120:123], v[160:163], v[184:187], v[120:123]
	v_mfma_f32_16x16x32_bf16 v[108:111], v[144:147], v[192:195], v[108:111]
	v_mfma_f32_16x16x32_bf16 v[104:107], v[160:163], v[192:195], v[104:107]
	v_mfma_f32_16x16x32_bf16 v[92:95], v[144:147], v[202:205], v[92:95]
	v_mfma_f32_16x16x32_bf16 v[88:91], v[160:163], v[202:205], v[88:91]
	v_mfma_f32_16x16x32_bf16 v[76:79], v[144:147], v[210:213], v[76:79]
	v_mfma_f32_16x16x32_bf16 v[72:75], v[160:163], v[210:213], v[72:75]
	v_mfma_f32_16x16x32_bf16 v[124:127], v[156:159], v[188:191], v[124:127]
	v_mfma_f32_16x16x32_bf16 v[120:123], v[164:167], v[188:191], v[120:123]
	v_mfma_f32_16x16x32_bf16 v[108:111], v[156:159], v[196:199], v[108:111]
	v_mfma_f32_16x16x32_bf16 v[104:107], v[164:167], v[196:199], v[104:107]
	v_mfma_f32_16x16x32_bf16 v[92:95], v[156:159], v[206:209], v[92:95]
	v_mfma_f32_16x16x32_bf16 v[88:91], v[164:167], v[206:209], v[88:91]
	v_mfma_f32_16x16x32_bf16 v[76:79], v[156:159], v[214:217], v[76:79]
	v_mfma_f32_16x16x32_bf16 v[72:75], v[164:167], v[214:217], v[72:75]
	v_mfma_f32_16x16x32_bf16 v[116:119], v[168:171], v[184:187], v[116:119]
	v_mfma_f32_16x16x32_bf16 v[112:115], v[176:179], v[184:187], v[112:115]
	v_mfma_f32_16x16x32_bf16 v[100:103], v[168:171], v[192:195], v[100:103]
	v_mfma_f32_16x16x32_bf16 v[96:99], v[176:179], v[192:195], v[96:99]
	v_mfma_f32_16x16x32_bf16 v[84:87], v[168:171], v[202:205], v[84:87]
	v_mfma_f32_16x16x32_bf16 v[80:83], v[176:179], v[202:205], v[80:83]
	v_mfma_f32_16x16x32_bf16 v[68:71], v[168:171], v[210:213], v[68:71]
	v_mfma_f32_16x16x32_bf16 v[64:67], v[176:179], v[210:213], v[64:67]
	v_mfma_f32_16x16x32_bf16 v[116:119], v[172:175], v[188:191], v[116:119]
	v_mfma_f32_16x16x32_bf16 v[112:115], v[180:183], v[188:191], v[112:115]
	v_mfma_f32_16x16x32_bf16 v[100:103], v[172:175], v[196:199], v[100:103]
	v_mfma_f32_16x16x32_bf16 v[96:99], v[180:183], v[196:199], v[96:99]
	v_mfma_f32_16x16x32_bf16 v[84:87], v[172:175], v[206:209], v[84:87]
	v_mfma_f32_16x16x32_bf16 v[80:83], v[180:183], v[206:209], v[80:83]
	v_mfma_f32_16x16x32_bf16 v[68:71], v[172:175], v[214:217], v[68:71]
	v_mfma_f32_16x16x32_bf16 v[64:67], v[180:183], v[214:217], v[64:67]
	s_barrier
	s_add_u32 s100, s36, 0x80
	s_addc_u32 s101, s37, 0
	s_add_u32 s58, s36, 0x100080
	s_addc_u32 s59, s37, 0
	s_add_u32 s98, s38, 0x80
	s_addc_u32 s99, s39, 0
	ds_read_b128 v[184:187], v155 offset:49152
	ds_read_b128 v[188:191], v155 offset:50176
	ds_read_b128 v[192:195], v155 offset:51200
	ds_read_b128 v[196:199], v155 offset:52224
	ds_read_b128 v[202:205], v155 offset:53248
	ds_read_b128 v[206:209], v155 offset:54272
	ds_read_b128 v[210:213], v155 offset:55296
	ds_read_b128 v[214:217], v155 offset:56320
	s_add_i32 m0, s31, 0x18000
	s_nop 0
	global_load_lds_dwordx4 v130, s[100:101]
	s_add_i32 m0, s31, 0x1a000
	s_nop 0
	global_load_lds_dwordx4 v134, s[100:101]
	s_add_i32 m0, s31, 0x1c000
	s_nop 0
	global_load_lds_dwordx4 v130, s[58:59]
	s_add_i32 m0, s31, 0x1e000
	s_nop 0
	global_load_lds_dwordx4 v134, s[58:59]
	s_add_i32 m0, s31, 0x8000
	s_nop 0
	global_load_lds_dwordx4 v128, s[98:99]
	s_add_i32 m0, s31, 0xa000
	s_nop 0
	global_load_lds_dwordx4 v132, s[98:99]
	s_waitcnt vmcnt(8)
	s_waitcnt lgkmcnt(0)
	s_barrier
	v_mfma_f32_16x16x32_bf16 v[60:63], v[144:147], v[184:187], v[60:63]
	v_mfma_f32_16x16x32_bf16 v[56:59], v[160:163], v[184:187], v[56:59]
	v_mfma_f32_16x16x32_bf16 v[44:47], v[144:147], v[192:195], v[44:47]
	v_mfma_f32_16x16x32_bf16 v[40:43], v[160:163], v[192:195], v[40:43]
	v_mfma_f32_16x16x32_bf16 v[28:31], v[144:147], v[202:205], v[28:31]
	v_mfma_f32_16x16x32_bf16 v[24:27], v[160:163], v[202:205], v[24:27]
	v_mfma_f32_16x16x32_bf16 v[12:15], v[144:147], v[210:213], v[12:15]
	v_mfma_f32_16x16x32_bf16 v[8:11], v[160:163], v[210:213], v[8:11]
	v_mfma_f32_16x16x32_bf16 v[60:63], v[156:159], v[188:191], v[60:63]
	v_mfma_f32_16x16x32_bf16 v[56:59], v[164:167], v[188:191], v[56:59]
	v_mfma_f32_16x16x32_bf16 v[44:47], v[156:159], v[196:199], v[44:47]
	v_mfma_f32_16x16x32_bf16 v[40:43], v[164:167], v[196:199], v[40:43]
	v_mfma_f32_16x16x32_bf16 v[28:31], v[156:159], v[206:209], v[28:31]
	v_mfma_f32_16x16x32_bf16 v[24:27], v[164:167], v[206:209], v[24:27]
	v_mfma_f32_16x16x32_bf16 v[12:15], v[156:159], v[214:217], v[12:15]
	v_mfma_f32_16x16x32_bf16 v[8:11], v[164:167], v[214:217], v[8:11]
	v_mfma_f32_16x16x32_bf16 v[52:55], v[168:171], v[184:187], v[52:55]
	v_mfma_f32_16x16x32_bf16 v[48:51], v[176:179], v[184:187], v[48:51]
	v_mfma_f32_16x16x32_bf16 v[36:39], v[168:171], v[192:195], v[36:39]
	v_mfma_f32_16x16x32_bf16 v[32:35], v[176:179], v[192:195], v[32:35]
	v_mfma_f32_16x16x32_bf16 v[20:23], v[168:171], v[202:205], v[20:23]
	v_mfma_f32_16x16x32_bf16 v[16:19], v[176:179], v[202:205], v[16:19]
	v_mfma_f32_16x16x32_bf16 v[4:7], v[168:171], v[210:213], v[4:7]
	v_mfma_f32_16x16x32_bf16 v[0:3], v[176:179], v[210:213], v[0:3]
	v_mfma_f32_16x16x32_bf16 v[52:55], v[172:175], v[188:191], v[52:55]
	v_mfma_f32_16x16x32_bf16 v[48:51], v[180:183], v[188:191], v[48:51]
	v_mfma_f32_16x16x32_bf16 v[36:39], v[172:175], v[196:199], v[36:39]
	v_mfma_f32_16x16x32_bf16 v[32:35], v[180:183], v[196:199], v[32:35]
	v_mfma_f32_16x16x32_bf16 v[20:23], v[172:175], v[206:209], v[20:23]
	v_mfma_f32_16x16x32_bf16 v[16:19], v[180:183], v[206:209], v[16:19]
	v_mfma_f32_16x16x32_bf16 v[4:7], v[172:175], v[214:217], v[4:7]
	v_mfma_f32_16x16x32_bf16 v[0:3], v[180:183], v[214:217], v[0:3]
	s_barrier
	s_add_i32 s57, s57, 2
	s_add_u32 s34, s34, 0x100
	s_addc_u32 s35, s35, 0
	s_add_u32 s55, s55, 0x100
	s_addc_u32 s56, s56, 0
	s_cmp_gt_u32 s57, 61
	s_cbranch_scc0 .LBB0_1299
	s_and_b64 vcc, exec, s[6:7]
	s_cbranch_vccz .LBB0_1302
	s_barrier

.LBB0_1409:
	ds_read_b128 v[128:131], v177 offset:0
	ds_read_b128 v[146:149], v177 offset:1024
	ds_read_b128 v[150:153], v177 offset:2048
	ds_read_b128 v[154:157], v177 offset:3072
	ds_read_b128 v[158:161], v178 offset:0
	ds_read_b128 v[162:165], v178 offset:1024
	ds_read_b128 v[166:169], v178 offset:2048
	ds_read_b128 v[170:173], v178 offset:3072
	s_add_i32 s70, s46, 2
	s_add_u32 s44, s42, 0x100
	s_addc_u32 s45, s43, 0
	s_cmp_eq_u32 s37, s46
	s_cselect_b32 s46, s40, s68
	s_cselect_b32 s49, s39, s45
	s_cselect_b32 s48, s38, s44
	s_cselect_b32 s47, s41, s69
	ds_read_b128 v[180:183], v179 offset:0
	ds_read_b128 v[184:187], v179 offset:1024
	ds_read_b128 v[188:191], v179 offset:2048
	ds_read_b128 v[192:195], v179 offset:3072
	ds_read_b128 v[196:199], v179 offset:4096
	ds_read_b128 v[202:205], v179 offset:5120
	ds_read_b128 v[206:209], v179 offset:6144
	ds_read_b128 v[210:213], v179 offset:7168
	s_add_i32 m0, s50, 0xc000
	s_nop 0
	global_load_lds_dwordx4 v140, s[42:43]
	s_add_i32 m0, s50, 0xe000
	s_nop 0
	global_load_lds_dwordx4 v142, s[42:43]
	s_waitcnt vmcnt(8)
	s_waitcnt lgkmcnt(0)
	s_barrier
	v_mfma_f32_16x16x32_bf16 v[124:127], v[128:131], v[180:183], v[124:127]
	v_mfma_f32_16x16x32_bf16 v[120:123], v[150:153], v[180:183], v[120:123]
	v_mfma_f32_16x16x32_bf16 v[108:111], v[128:131], v[188:191], v[108:111]
	v_mfma_f32_16x16x32_bf16 v[104:107], v[150:153], v[188:191], v[104:107]
	v_mfma_f32_16x16x32_bf16 v[92:95], v[128:131], v[196:199], v[92:95]
	v_mfma_f32_16x16x32_bf16 v[88:91], v[150:153], v[196:199], v[88:91]
	v_mfma_f32_16x16x32_bf16 v[76:79], v[128:131], v[206:209], v[76:79]
	v_mfma_f32_16x16x32_bf16 v[72:75], v[150:153], v[206:209], v[72:75]
	v_mfma_f32_16x16x32_bf16 v[124:127], v[146:149], v[184:187], v[124:127]
	v_mfma_f32_16x16x32_bf16 v[120:123], v[154:157], v[184:187], v[120:123]
	v_mfma_f32_16x16x32_bf16 v[108:111], v[146:149], v[192:195], v[108:111]
	v_mfma_f32_16x16x32_bf16 v[104:107], v[154:157], v[192:195], v[104:107]
	v_mfma_f32_16x16x32_bf16 v[92:95], v[146:149], v[202:205], v[92:95]
	v_mfma_f32_16x16x32_bf16 v[88:91], v[154:157], v[202:205], v[88:91]
	v_mfma_f32_16x16x32_bf16 v[76:79], v[146:149], v[210:213], v[76:79]
	v_mfma_f32_16x16x32_bf16 v[72:75], v[154:157], v[210:213], v[72:75]
	v_mfma_f32_16x16x32_bf16 v[116:119], v[158:161], v[180:183], v[116:119]
	v_mfma_f32_16x16x32_bf16 v[112:115], v[166:169], v[180:183], v[112:115]
	v_mfma_f32_16x16x32_bf16 v[100:103], v[158:161], v[188:191], v[100:103]
	v_mfma_f32_16x16x32_bf16 v[96:99], v[166:169], v[188:191], v[96:99]
	v_mfma_f32_16x16x32_bf16 v[84:87], v[158:161], v[196:199], v[84:87]
	v_mfma_f32_16x16x32_bf16 v[80:83], v[166:169], v[196:199], v[80:83]
	v_mfma_f32_16x16x32_bf16 v[68:71], v[158:161], v[206:209], v[68:71]
	v_mfma_f32_16x16x32_bf16 v[64:67], v[166:169], v[206:209], v[64:67]
	v_mfma_f32_16x16x32_bf16 v[116:119], v[162:165], v[184:187], v[116:119]
	v_mfma_f32_16x16x32_bf16 v[112:115], v[170:173], v[184:187], v[112:115]
	v_mfma_f32_16x16x32_bf16 v[100:103], v[162:165], v[192:195], v[100:103]
	v_mfma_f32_16x16x32_bf16 v[96:99], v[170:173], v[192:195], v[96:99]
	v_mfma_f32_16x16x32_bf16 v[84:87], v[162:165], v[202:205], v[84:87]
	v_mfma_f32_16x16x32_bf16 v[80:83], v[170:173], v[202:205], v[80:83]
	v_mfma_f32_16x16x32_bf16 v[68:71], v[162:165], v[210:213], v[68:71]
	v_mfma_f32_16x16x32_bf16 v[64:67], v[170:173], v[210:213], v[64:67]
	s_barrier
	s_add_u32 s42, s46, 0x2b0000
	s_addc_u32 s43, s47, 0
	ds_read_b128 v[180:183], v179 offset:16384
	ds_read_b128 v[184:187], v179 offset:17408
	ds_read_b128 v[188:191], v179 offset:18432
	ds_read_b128 v[192:195], v179 offset:19456
	ds_read_b128 v[196:199], v179 offset:20480
	ds_read_b128 v[202:205], v179 offset:21504
	ds_read_b128 v[206:209], v179 offset:22528
	ds_read_b128 v[210:213], v179 offset:23552
	s_add_i32 m0, s50, 0x10000
	s_nop 0
	global_load_lds_dwordx4 v134, s[46:47]
	s_add_i32 m0, s50, 0x12000
	s_nop 0
	global_load_lds_dwordx4 v138, s[46:47]
	s_add_i32 m0, s50, 0x14000
	s_nop 0
	global_load_lds_dwordx4 v134, s[42:43]
	s_add_i32 m0, s50, 0x16000
	s_nop 0
	global_load_lds_dwordx4 v138, s[42:43]
	s_add_i32 m0, s50, 0x0
	s_nop 0
	global_load_lds_dwordx4 v132, s[48:49]
	s_add_i32 m0, s50, 0x2000
	s_nop 0
	global_load_lds_dwordx4 v136, s[48:49]
	s_waitcnt vmcnt(8)
	s_waitcnt lgkmcnt(0)
	s_barrier
	v_mfma_f32_16x16x32_bf16 v[60:63], v[128:131], v[180:183], v[60:63]
	v_mfma_f32_16x16x32_bf16 v[56:59], v[150:153], v[180:183], v[56:59]
	v_mfma_f32_16x16x32_bf16 v[44:47], v[128:131], v[188:191], v[44:47]
	v_mfma_f32_16x16x32_bf16 v[40:43], v[150:153], v[188:191], v[40:43]
	v_mfma_f32_16x16x32_bf16 v[28:31], v[128:131], v[196:199], v[28:31]
	v_mfma_f32_16x16x32_bf16 v[24:27], v[150:153], v[196:199], v[24:27]
	v_mfma_f32_16x16x32_bf16 v[12:15], v[128:131], v[206:209], v[12:15]
	v_mfma_f32_16x16x32_bf16 v[8:11], v[150:153], v[206:209], v[8:11]
	v_mfma_f32_16x16x32_bf16 v[60:63], v[146:149], v[184:187], v[60:63]
	v_mfma_f32_16x16x32_bf16 v[56:59], v[154:157], v[184:187], v[56:59]
	v_mfma_f32_16x16x32_bf16 v[44:47], v[146:149], v[192:195], v[44:47]
	v_mfma_f32_16x16x32_bf16 v[40:43], v[154:157], v[192:195], v[40:43]
	v_mfma_f32_16x16x32_bf16 v[28:31], v[146:149], v[202:205], v[28:31]
	v_mfma_f32_16x16x32_bf16 v[24:27], v[154:157], v[202:205], v[24:27]
	v_mfma_f32_16x16x32_bf16 v[12:15], v[146:149], v[210:213], v[12:15]
	v_mfma_f32_16x16x32_bf16 v[8:11], v[154:157], v[210:213], v[8:11]
	v_mfma_f32_16x16x32_bf16 v[52:55], v[158:161], v[180:183], v[52:55]
	v_mfma_f32_16x16x32_bf16 v[48:51], v[166:169], v[180:183], v[48:51]
	v_mfma_f32_16x16x32_bf16 v[36:39], v[158:161], v[188:191], v[36:39]
	v_mfma_f32_16x16x32_bf16 v[32:35], v[166:169], v[188:191], v[32:35]
	v_mfma_f32_16x16x32_bf16 v[20:23], v[158:161], v[196:199], v[20:23]
	v_mfma_f32_16x16x32_bf16 v[16:19], v[166:169], v[196:199], v[16:19]
	v_mfma_f32_16x16x32_bf16 v[4:7], v[158:161], v[206:209], v[4:7]
	v_mfma_f32_16x16x32_bf16 v[0:3], v[166:169], v[206:209], v[0:3]
	v_mfma_f32_16x16x32_bf16 v[52:55], v[162:165], v[184:187], v[52:55]
	v_mfma_f32_16x16x32_bf16 v[48:51], v[170:173], v[184:187], v[48:51]
	v_mfma_f32_16x16x32_bf16 v[36:39], v[162:165], v[192:195], v[36:39]
	v_mfma_f32_16x16x32_bf16 v[32:35], v[170:173], v[192:195], v[32:35]
	v_mfma_f32_16x16x32_bf16 v[20:23], v[162:165], v[202:205], v[20:23]
	v_mfma_f32_16x16x32_bf16 v[16:19], v[170:173], v[202:205], v[16:19]
	v_mfma_f32_16x16x32_bf16 v[4:7], v[162:165], v[210:213], v[4:7]
	v_mfma_f32_16x16x32_bf16 v[0:3], v[170:173], v[210:213], v[0:3]
	s_barrier
	s_add_u32 s98, s48, 0x2b0000
	s_addc_u32 s99, s49, 0
	ds_read_b128 v[128:131], v177 offset:32768
	ds_read_b128 v[146:149], v177 offset:33792
	ds_read_b128 v[150:153], v177 offset:34816
	ds_read_b128 v[154:157], v177 offset:35840
	ds_read_b128 v[158:161], v178 offset:32768
	ds_read_b128 v[162:165], v178 offset:33792
	ds_read_b128 v[166:169], v178 offset:34816
	ds_read_b128 v[170:173], v178 offset:35840
	ds_read_b128 v[180:183], v179 offset:32768
	ds_read_b128 v[184:187], v179 offset:33792
	ds_read_b128 v[188:191], v179 offset:34816
	ds_read_b128 v[192:195], v179 offset:35840
	ds_read_b128 v[196:199], v179 offset:36864
	ds_read_b128 v[202:205], v179 offset:37888
	ds_read_b128 v[206:209], v179 offset:38912
	ds_read_b128 v[210:213], v179 offset:39936
	s_add_i32 m0, s50, 0x4000
	s_nop 0
	global_load_lds_dwordx4 v132, s[98:99]
	s_add_i32 m0, s50, 0x6000
	s_nop 0
	global_load_lds_dwordx4 v136, s[98:99]
	s_waitcnt vmcnt(8)
	s_waitcnt lgkmcnt(0)
	s_barrier
	v_mfma_f32_16x16x32_bf16 v[124:127], v[128:131], v[180:183], v[124:127]
	v_mfma_f32_16x16x32_bf16 v[120:123], v[150:153], v[180:183], v[120:123]
	v_mfma_f32_16x16x32_bf16 v[108:111], v[128:131], v[188:191], v[108:111]
	v_mfma_f32_16x16x32_bf16 v[104:107], v[150:153], v[188:191], v[104:107]
	v_mfma_f32_16x16x32_bf16 v[92:95], v[128:131], v[196:199], v[92:95]
	v_mfma_f32_16x16x32_bf16 v[88:91], v[150:153], v[196:199], v[88:91]
	v_mfma_f32_16x16x32_bf16 v[76:79], v[128:131], v[206:209], v[76:79]
	v_mfma_f32_16x16x32_bf16 v[72:75], v[150:153], v[206:209], v[72:75]
	v_mfma_f32_16x16x32_bf16 v[124:127], v[146:149], v[184:187], v[124:127]
	v_mfma_f32_16x16x32_bf16 v[120:123], v[154:157], v[184:187], v[120:123]
	v_mfma_f32_16x16x32_bf16 v[108:111], v[146:149], v[192:195], v[108:111]
	v_mfma_f32_16x16x32_bf16 v[104:107], v[154:157], v[192:195], v[104:107]
	v_mfma_f32_16x16x32_bf16 v[92:95], v[146:149], v[202:205], v[92:95]
	v_mfma_f32_16x16x32_bf16 v[88:91], v[154:157], v[202:205], v[88:91]
	v_mfma_f32_16x16x32_bf16 v[76:79], v[146:149], v[210:213], v[76:79]
	v_mfma_f32_16x16x32_bf16 v[72:75], v[154:157], v[210:213], v[72:75]
	v_mfma_f32_16x16x32_bf16 v[116:119], v[158:161], v[180:183], v[116:119]
	v_mfma_f32_16x16x32_bf16 v[112:115], v[166:169], v[180:183], v[112:115]
	v_mfma_f32_16x16x32_bf16 v[100:103], v[158:161], v[188:191], v[100:103]
	v_mfma_f32_16x16x32_bf16 v[96:99], v[166:169], v[188:191], v[96:99]
	v_mfma_f32_16x16x32_bf16 v[84:87], v[158:161], v[196:199], v[84:87]
	v_mfma_f32_16x16x32_bf16 v[80:83], v[166:169], v[196:199], v[80:83]
	v_mfma_f32_16x16x32_bf16 v[68:71], v[158:161], v[206:209], v[68:71]
	v_mfma_f32_16x16x32_bf16 v[64:67], v[166:169], v[206:209], v[64:67]
	v_mfma_f32_16x16x32_bf16 v[116:119], v[162:165], v[184:187], v[116:119]
	v_mfma_f32_16x16x32_bf16 v[112:115], v[170:173], v[184:187], v[112:115]
	v_mfma_f32_16x16x32_bf16 v[100:103], v[162:165], v[192:195], v[100:103]
	v_mfma_f32_16x16x32_bf16 v[96:99], v[170:173], v[192:195], v[96:99]
	v_mfma_f32_16x16x32_bf16 v[84:87], v[162:165], v[202:205], v[84:87]
	v_mfma_f32_16x16x32_bf16 v[80:83], v[170:173], v[202:205], v[80:83]
	v_mfma_f32_16x16x32_bf16 v[68:71], v[162:165], v[210:213], v[68:71]
	v_mfma_f32_16x16x32_bf16 v[64:67], v[170:173], v[210:213], v[64:67]
	s_barrier
	s_add_u32 s100, s46, 0x80
	s_addc_u32 s101, s47, 0
	s_add_u32 s42, s46, 0x2b0080
	s_addc_u32 s43, s47, 0
	s_add_u32 s98, s48, 0x80
	s_addc_u32 s99, s49, 0
	ds_read_b128 v[180:183], v179 offset:49152
	ds_read_b128 v[184:187], v179 offset:50176
	ds_read_b128 v[188:191], v179 offset:51200
	ds_read_b128 v[192:195], v179 offset:52224
	ds_read_b128 v[196:199], v179 offset:53248
	ds_read_b128 v[202:205], v179 offset:54272
	ds_read_b128 v[206:209], v179 offset:55296
	ds_read_b128 v[210:213], v179 offset:56320
	s_add_i32 m0, s50, 0x18000
	s_nop 0
	global_load_lds_dwordx4 v134, s[100:101]
	s_add_i32 m0, s50, 0x1a000
	s_nop 0
	global_load_lds_dwordx4 v138, s[100:101]
	s_add_i32 m0, s50, 0x1c000
	s_nop 0
	global_load_lds_dwordx4 v134, s[42:43]
	s_add_i32 m0, s50, 0x1e000
	s_nop 0
	global_load_lds_dwordx4 v138, s[42:43]
	s_add_i32 m0, s50, 0x8000
	s_nop 0
	global_load_lds_dwordx4 v132, s[98:99]
	s_add_i32 m0, s50, 0xa000
	s_nop 0
	global_load_lds_dwordx4 v136, s[98:99]
	s_waitcnt vmcnt(8)
	s_waitcnt lgkmcnt(0)
	s_barrier
	v_mfma_f32_16x16x32_bf16 v[60:63], v[128:131], v[180:183], v[60:63]
	v_mfma_f32_16x16x32_bf16 v[56:59], v[150:153], v[180:183], v[56:59]
	v_mfma_f32_16x16x32_bf16 v[44:47], v[128:131], v[188:191], v[44:47]
	v_mfma_f32_16x16x32_bf16 v[40:43], v[150:153], v[188:191], v[40:43]
	v_mfma_f32_16x16x32_bf16 v[28:31], v[128:131], v[196:199], v[28:31]
	v_mfma_f32_16x16x32_bf16 v[24:27], v[150:153], v[196:199], v[24:27]
	v_mfma_f32_16x16x32_bf16 v[12:15], v[128:131], v[206:209], v[12:15]
	v_mfma_f32_16x16x32_bf16 v[8:11], v[150:153], v[206:209], v[8:11]
	v_mfma_f32_16x16x32_bf16 v[60:63], v[146:149], v[184:187], v[60:63]
	v_mfma_f32_16x16x32_bf16 v[56:59], v[154:157], v[184:187], v[56:59]
	v_mfma_f32_16x16x32_bf16 v[44:47], v[146:149], v[192:195], v[44:47]
	v_mfma_f32_16x16x32_bf16 v[40:43], v[154:157], v[192:195], v[40:43]
	v_mfma_f32_16x16x32_bf16 v[28:31], v[146:149], v[202:205], v[28:31]
	v_mfma_f32_16x16x32_bf16 v[24:27], v[154:157], v[202:205], v[24:27]
	v_mfma_f32_16x16x32_bf16 v[12:15], v[146:149], v[210:213], v[12:15]
	v_mfma_f32_16x16x32_bf16 v[8:11], v[154:157], v[210:213], v[8:11]
	v_mfma_f32_16x16x32_bf16 v[52:55], v[158:161], v[180:183], v[52:55]
	v_mfma_f32_16x16x32_bf16 v[48:51], v[166:169], v[180:183], v[48:51]
	v_mfma_f32_16x16x32_bf16 v[36:39], v[158:161], v[188:191], v[36:39]
	v_mfma_f32_16x16x32_bf16 v[32:35], v[166:169], v[188:191], v[32:35]
	v_mfma_f32_16x16x32_bf16 v[20:23], v[158:161], v[196:199], v[20:23]
	v_mfma_f32_16x16x32_bf16 v[16:19], v[166:169], v[196:199], v[16:19]
	v_mfma_f32_16x16x32_bf16 v[4:7], v[158:161], v[206:209], v[4:7]
	v_mfma_f32_16x16x32_bf16 v[0:3], v[166:169], v[206:209], v[0:3]
	v_mfma_f32_16x16x32_bf16 v[52:55], v[162:165], v[184:187], v[52:55]
	v_mfma_f32_16x16x32_bf16 v[48:51], v[170:173], v[184:187], v[48:51]
	v_mfma_f32_16x16x32_bf16 v[36:39], v[162:165], v[192:195], v[36:39]
	v_mfma_f32_16x16x32_bf16 v[32:35], v[170:173], v[192:195], v[32:35]
	v_mfma_f32_16x16x32_bf16 v[20:23], v[162:165], v[202:205], v[20:23]
	v_mfma_f32_16x16x32_bf16 v[16:19], v[170:173], v[202:205], v[16:19]
	v_mfma_f32_16x16x32_bf16 v[4:7], v[162:165], v[210:213], v[4:7]
	v_mfma_f32_16x16x32_bf16 v[0:3], v[170:173], v[210:213], v[0:3]
	s_barrier
	s_add_u32 s68, s68, 0x100
	s_addc_u32 s69, s69, 0
	s_cmp_ge_i32 s70, s67
	s_mov_b64 s[42:43], s[44:45]
	s_mov_b32 s46, s70
	s_cbranch_scc0 .LBB0_1409
	s_and_b64 vcc, exec, s[14:15]
	s_cbranch_vccz .LBB0_1412
